# k39 + stacked sync trims: scalar arrive atomics, scalar polls at in-epilogue and XCC barriers, s_setprio raised before the M-phase barrier
# speedup vs baseline: 1.0022x; 1.0022x over previous
.LBB0_444:
	s_add_u32 s48, s46, 0x20080
	s_addc_u32 s49, s47, 0
	s_add_u32 s25, s50, 0x100
	s_addc_u32 s64, s51, 0
	s_mov_b32 s65, -2
	s_add_u32 s46, s48, 0xfffe0080
	s_addc_u32 s47, s49, -1
	s_add_i32 s84, 0, 0x10000
	s_cmp_eq_u32 s65, 4
	s_cselect_b32 s47, s15, s47
	s_cselect_b32 s46, s14, s46
	v_add_u32_e32 v0, s84, v147
	s_cselect_b32 s51, s17, s64
	s_cselect_b32 s50, s16, s25
	s_add_i32 s86, 0, 0x14000
	ds_read_b128 v[150:153], v0
	ds_read_b128 v[154:157], v0 offset:1024
	ds_read_b128 v[158:161], v0 offset:2048
	ds_read_b128 v[162:165], v0 offset:3072
	ds_read_b128 v[166:169], v0 offset:16384
	ds_read_b128 v[170:173], v0 offset:17408
	ds_read_b128 v[174:177], v0 offset:18432
	ds_read_b128 v[178:181], v0 offset:19456
	ds_read_b128 v[182:185], v148
	ds_read_b128 v[186:189], v148 offset:1024
	ds_read_b128 v[190:193], v148 offset:2048
	ds_read_b128 v[194:197], v148 offset:3072
	ds_read_b128 v[198:201], v148 offset:4096
	ds_read_b128 v[202:205], v148 offset:5120
	ds_read_b128 v[206:209], v148 offset:6144
	ds_read_b128 v[210:213], v148 offset:7168
	s_add_i32 m0, s59, 0xc000
	s_nop 0
	global_load_lds_dwordx4 v132, s[48:49]
	s_add_i32 m0, s59, 0xe000
	s_nop 0
	global_load_lds_dwordx4 v133, s[48:49]
	s_waitcnt vmcnt(8)
	s_waitcnt lgkmcnt(0)
	s_setprio 1
	s_barrier
	v_mfma_i32_16x16x64_i8 v[126:129], v[150:153], v[182:185], 0
	v_mfma_i32_16x16x64_i8 v[122:125], v[158:161], v[182:185], 0
	v_mfma_i32_16x16x64_i8 v[110:113], v[150:153], v[190:193], 0
	v_mfma_i32_16x16x64_i8 v[106:109], v[158:161], v[190:193], 0
	v_mfma_i32_16x16x64_i8 v[94:97], v[150:153], v[198:201], 0
	v_mfma_i32_16x16x64_i8 v[90:93], v[158:161], v[198:201], 0
	v_mfma_i32_16x16x64_i8 v[78:81], v[150:153], v[206:209], 0
	v_mfma_i32_16x16x64_i8 v[74:77], v[158:161], v[206:209], 0
	v_mfma_i32_16x16x64_i8 v[126:129], v[154:157], v[186:189], v[126:129]
	v_mfma_i32_16x16x64_i8 v[122:125], v[162:165], v[186:189], v[122:125]
	v_mfma_i32_16x16x64_i8 v[110:113], v[154:157], v[194:197], v[110:113]
	v_mfma_i32_16x16x64_i8 v[106:109], v[162:165], v[194:197], v[106:109]
	v_mfma_i32_16x16x64_i8 v[94:97], v[154:157], v[202:205], v[94:97]
	v_mfma_i32_16x16x64_i8 v[90:93], v[162:165], v[202:205], v[90:93]
	v_mfma_i32_16x16x64_i8 v[78:81], v[154:157], v[210:213], v[78:81]
	v_mfma_i32_16x16x64_i8 v[74:77], v[162:165], v[210:213], v[74:77]
	s_setprio 0
	s_setprio 1
	v_mfma_i32_16x16x64_i8 v[118:121], v[166:169], v[182:185], 0
	v_mfma_i32_16x16x64_i8 v[114:117], v[174:177], v[182:185], 0
	v_mfma_i32_16x16x64_i8 v[102:105], v[166:169], v[190:193], 0
	v_mfma_i32_16x16x64_i8 v[98:101], v[174:177], v[190:193], 0
	v_mfma_i32_16x16x64_i8 v[86:89], v[166:169], v[198:201], 0
	v_mfma_i32_16x16x64_i8 v[82:85], v[174:177], v[198:201], 0
	v_mfma_i32_16x16x64_i8 v[70:73], v[166:169], v[206:209], 0
	v_mfma_i32_16x16x64_i8 v[66:69], v[174:177], v[206:209], 0
	v_mfma_i32_16x16x64_i8 v[118:121], v[170:173], v[186:189], v[118:121]
	v_mfma_i32_16x16x64_i8 v[114:117], v[178:181], v[186:189], v[114:117]
	v_mfma_i32_16x16x64_i8 v[102:105], v[170:173], v[194:197], v[102:105]
	v_mfma_i32_16x16x64_i8 v[98:101], v[178:181], v[194:197], v[98:101]
	v_mfma_i32_16x16x64_i8 v[86:89], v[170:173], v[202:205], v[86:89]
	v_mfma_i32_16x16x64_i8 v[82:85], v[178:181], v[202:205], v[82:85]
	v_mfma_i32_16x16x64_i8 v[70:73], v[170:173], v[210:213], v[70:73]
	v_mfma_i32_16x16x64_i8 v[66:69], v[178:181], v[210:213], v[66:69]
	s_setprio 0
	s_barrier
	s_add_i32 s84, s84, s40
	ds_read_b128 v[182:185], v148 offset:16384
	ds_read_b128 v[186:189], v148 offset:17408
	ds_read_b128 v[190:193], v148 offset:18432
	ds_read_b128 v[194:197], v148 offset:19456
	ds_read_b128 v[198:201], v148 offset:20480
	ds_read_b128 v[202:205], v148 offset:21504
	ds_read_b128 v[206:209], v148 offset:22528
	ds_read_b128 v[210:213], v148 offset:23552
	s_mov_b32 m0, s84
	s_nop 0
	global_load_lds_dwordx4 v143, s[50:51]
	s_add_i32 m0, s84, 0x2000
	s_add_u32 s84, s50, 0x20000
	global_load_lds_dwordx4 v144, s[50:51]
	s_addc_u32 s85, s51, 0
	s_add_i32 s86, s86, s40
	s_mov_b32 m0, s86
	s_nop 0
	global_load_lds_dwordx4 v143, s[84:85]
	s_add_i32 m0, s86, 0x2000
	s_nop 0
	global_load_lds_dwordx4 v144, s[84:85]
	s_mov_b32 m0, s59
	s_nop 0
	global_load_lds_dwordx4 v132, s[46:47]
	s_mov_b32 m0, s60
	s_nop 0
	global_load_lds_dwordx4 v133, s[46:47]
	s_waitcnt vmcnt(8)
	s_waitcnt lgkmcnt(0)
	s_setprio 1
	s_barrier
	v_mfma_i32_16x16x64_i8 v[62:65], v[150:153], v[182:185], 0
	v_mfma_i32_16x16x64_i8 v[58:61], v[158:161], v[182:185], 0
	v_mfma_i32_16x16x64_i8 v[46:49], v[150:153], v[190:193], 0
	v_mfma_i32_16x16x64_i8 v[42:45], v[158:161], v[190:193], 0
	v_mfma_i32_16x16x64_i8 v[30:33], v[150:153], v[198:201], 0
	v_mfma_i32_16x16x64_i8 v[26:29], v[158:161], v[198:201], 0
	v_mfma_i32_16x16x64_i8 v[14:17], v[150:153], v[206:209], 0
	v_mfma_i32_16x16x64_i8 v[10:13], v[158:161], v[206:209], 0
	v_mfma_i32_16x16x64_i8 v[62:65], v[154:157], v[186:189], v[62:65]
	v_mfma_i32_16x16x64_i8 v[58:61], v[162:165], v[186:189], v[58:61]
	v_mfma_i32_16x16x64_i8 v[46:49], v[154:157], v[194:197], v[46:49]
	v_mfma_i32_16x16x64_i8 v[42:45], v[162:165], v[194:197], v[42:45]
	v_mfma_i32_16x16x64_i8 v[30:33], v[154:157], v[202:205], v[30:33]
	v_mfma_i32_16x16x64_i8 v[26:29], v[162:165], v[202:205], v[26:29]
	v_mfma_i32_16x16x64_i8 v[14:17], v[154:157], v[210:213], v[14:17]
	v_mfma_i32_16x16x64_i8 v[10:13], v[162:165], v[210:213], v[10:13]
	s_setprio 0
	s_setprio 1
	v_mfma_i32_16x16x64_i8 v[54:57], v[166:169], v[182:185], 0
	v_mfma_i32_16x16x64_i8 v[50:53], v[174:177], v[182:185], 0
	v_mfma_i32_16x16x64_i8 v[38:41], v[166:169], v[190:193], 0
	v_mfma_i32_16x16x64_i8 v[34:37], v[174:177], v[190:193], 0
	v_mfma_i32_16x16x64_i8 v[22:25], v[166:169], v[198:201], 0
	v_mfma_i32_16x16x64_i8 v[18:21], v[174:177], v[198:201], 0
	v_mfma_i32_16x16x64_i8 v[6:9], v[166:169], v[206:209], 0
	v_mfma_i32_16x16x64_i8 v[2:5], v[174:177], v[206:209], 0
	v_mfma_i32_16x16x64_i8 v[54:57], v[170:173], v[186:189], v[54:57]
	v_mfma_i32_16x16x64_i8 v[50:53], v[178:181], v[186:189], v[50:53]
	v_mfma_i32_16x16x64_i8 v[38:41], v[170:173], v[194:197], v[38:41]
	v_mfma_i32_16x16x64_i8 v[34:37], v[178:181], v[194:197], v[34:37]
	v_mfma_i32_16x16x64_i8 v[22:25], v[170:173], v[202:205], v[22:25]
	v_mfma_i32_16x16x64_i8 v[18:21], v[178:181], v[202:205], v[18:21]
	v_mfma_i32_16x16x64_i8 v[6:9], v[170:173], v[210:213], v[6:9]
	v_mfma_i32_16x16x64_i8 v[2:5], v[178:181], v[210:213], v[2:5]
	s_setprio 0
	s_barrier
	s_add_i32 s86, 0, 0x18000
	s_add_i32 s87, 0, 0x1c000
	ds_read_b128 v[150:153], v0 offset:32768
	ds_read_b128 v[154:157], v0 offset:33792
	ds_read_b128 v[158:161], v0 offset:34816
	ds_read_b128 v[162:165], v0 offset:35840
	ds_read_b128 v[166:169], v0 offset:49152
	ds_read_b128 v[170:173], v0 offset:50176
	ds_read_b128 v[174:177], v0 offset:51200
	ds_read_b128 v[178:181], v0 offset:52224
	s_add_u32 s84, s46, 0x20000
	s_mov_b32 m0, s61
	ds_read_b128 v[182:185], v148 offset:32768
	ds_read_b128 v[186:189], v148 offset:33792
	ds_read_b128 v[190:193], v148 offset:34816
	ds_read_b128 v[194:197], v148 offset:35840
	ds_read_b128 v[198:201], v148 offset:36864
	ds_read_b128 v[202:205], v148 offset:37888
	ds_read_b128 v[206:209], v148 offset:38912
	ds_read_b128 v[210:213], v148 offset:39936
	s_addc_u32 s85, s47, 0
	s_nop 0
	global_load_lds_dwordx4 v132, s[84:85]
	s_mov_b32 m0, s66
	s_nop 0
	global_load_lds_dwordx4 v133, s[84:85]
	s_waitcnt vmcnt(8)
	s_waitcnt lgkmcnt(0)
	s_setprio 1
	s_barrier
	v_mfma_i32_16x16x64_i8 v[126:129], v[150:153], v[182:185], v[126:129]
	v_mfma_i32_16x16x64_i8 v[122:125], v[158:161], v[182:185], v[122:125]
	v_mfma_i32_16x16x64_i8 v[110:113], v[150:153], v[190:193], v[110:113]
	v_mfma_i32_16x16x64_i8 v[106:109], v[158:161], v[190:193], v[106:109]
	v_mfma_i32_16x16x64_i8 v[94:97], v[150:153], v[198:201], v[94:97]
	v_mfma_i32_16x16x64_i8 v[90:93], v[158:161], v[198:201], v[90:93]
	v_mfma_i32_16x16x64_i8 v[78:81], v[150:153], v[206:209], v[78:81]
	v_mfma_i32_16x16x64_i8 v[74:77], v[158:161], v[206:209], v[74:77]
	v_mfma_i32_16x16x64_i8 v[126:129], v[154:157], v[186:189], v[126:129]
	v_mfma_i32_16x16x64_i8 v[122:125], v[162:165], v[186:189], v[122:125]
	v_mfma_i32_16x16x64_i8 v[110:113], v[154:157], v[194:197], v[110:113]
	v_mfma_i32_16x16x64_i8 v[106:109], v[162:165], v[194:197], v[106:109]
	v_mfma_i32_16x16x64_i8 v[94:97], v[154:157], v[202:205], v[94:97]
	v_mfma_i32_16x16x64_i8 v[90:93], v[162:165], v[202:205], v[90:93]
	v_mfma_i32_16x16x64_i8 v[78:81], v[154:157], v[210:213], v[78:81]
	v_mfma_i32_16x16x64_i8 v[74:77], v[162:165], v[210:213], v[74:77]
	s_setprio 0
	s_setprio 1
	v_mfma_i32_16x16x64_i8 v[118:121], v[166:169], v[182:185], v[118:121]
	v_mfma_i32_16x16x64_i8 v[114:117], v[174:177], v[182:185], v[114:117]
	v_mfma_i32_16x16x64_i8 v[102:105], v[166:169], v[190:193], v[102:105]
	v_mfma_i32_16x16x64_i8 v[98:101], v[174:177], v[190:193], v[98:101]
	v_mfma_i32_16x16x64_i8 v[86:89], v[166:169], v[198:201], v[86:89]
	v_mfma_i32_16x16x64_i8 v[82:85], v[174:177], v[198:201], v[82:85]
	v_mfma_i32_16x16x64_i8 v[70:73], v[166:169], v[206:209], v[70:73]
	v_mfma_i32_16x16x64_i8 v[66:69], v[174:177], v[206:209], v[66:69]
	v_mfma_i32_16x16x64_i8 v[118:121], v[170:173], v[186:189], v[118:121]
	v_mfma_i32_16x16x64_i8 v[114:117], v[178:181], v[186:189], v[114:117]
	v_mfma_i32_16x16x64_i8 v[102:105], v[170:173], v[194:197], v[102:105]
	v_mfma_i32_16x16x64_i8 v[98:101], v[178:181], v[194:197], v[98:101]
	v_mfma_i32_16x16x64_i8 v[86:89], v[170:173], v[202:205], v[86:89]
	v_mfma_i32_16x16x64_i8 v[82:85], v[178:181], v[202:205], v[82:85]
	v_mfma_i32_16x16x64_i8 v[70:73], v[170:173], v[210:213], v[70:73]
	v_mfma_i32_16x16x64_i8 v[66:69], v[178:181], v[210:213], v[66:69]
	s_setprio 0
	s_barrier
	ds_read_b128 v[182:185], v148 offset:49152
	ds_read_b128 v[186:189], v148 offset:50176
	ds_read_b128 v[190:193], v148 offset:51200
	ds_read_b128 v[194:197], v148 offset:52224
	ds_read_b128 v[198:201], v148 offset:53248
	ds_read_b128 v[202:205], v148 offset:54272
	ds_read_b128 v[206:209], v148 offset:55296
	ds_read_b128 v[210:213], v148 offset:56320
	s_add_i32 s84, s86, s40
	s_add_u32 s100, s50, s38
	s_addc_u32 s101, s51, s39
	s_mov_b32 m0, s84
	s_nop 0
	global_load_lds_dwordx4 v143, s[100:101]
	s_add_i32 m0, s84, 0x2000
	s_nop 0
	s_add_u32 s50, s50, 0x20080
	s_addc_u32 s51, s51, 0
	s_add_i32 s84, s87, s40
	global_load_lds_dwordx4 v144, s[100:101]
	s_mov_b32 m0, s84
	s_nop 0
	global_load_lds_dwordx4 v143, s[50:51]
	s_add_i32 m0, s84, 0x2000
	s_nop 0
	global_load_lds_dwordx4 v144, s[50:51]
	s_mov_b32 m0, s75
	s_add_u32 s100, s46, s38
	s_addc_u32 s101, s47, s39
	v_mov_b32_e32 v0, v133
	global_load_lds_dwordx4 v132, s[100:101]
	s_mov_b32 m0, s78
	s_nop 0
	global_load_lds_dwordx4 v133, s[100:101]
	s_waitcnt vmcnt(8)
	s_waitcnt lgkmcnt(0)
	s_setprio 1
	s_barrier
	v_mfma_i32_16x16x64_i8 v[62:65], v[150:153], v[182:185], v[62:65]
	v_mfma_i32_16x16x64_i8 v[58:61], v[158:161], v[182:185], v[58:61]
	v_mfma_i32_16x16x64_i8 v[46:49], v[150:153], v[190:193], v[46:49]
	v_mfma_i32_16x16x64_i8 v[42:45], v[158:161], v[190:193], v[42:45]
	v_mfma_i32_16x16x64_i8 v[30:33], v[150:153], v[198:201], v[30:33]
	v_mfma_i32_16x16x64_i8 v[26:29], v[158:161], v[198:201], v[26:29]
	v_mfma_i32_16x16x64_i8 v[14:17], v[150:153], v[206:209], v[14:17]
	v_mfma_i32_16x16x64_i8 v[10:13], v[158:161], v[206:209], v[10:13]
	v_mfma_i32_16x16x64_i8 v[62:65], v[154:157], v[186:189], v[62:65]
	v_mfma_i32_16x16x64_i8 v[58:61], v[162:165], v[186:189], v[58:61]
	v_mfma_i32_16x16x64_i8 v[46:49], v[154:157], v[194:197], v[46:49]
	v_mfma_i32_16x16x64_i8 v[42:45], v[162:165], v[194:197], v[42:45]
	v_mfma_i32_16x16x64_i8 v[30:33], v[154:157], v[202:205], v[30:33]
	v_mfma_i32_16x16x64_i8 v[26:29], v[162:165], v[202:205], v[26:29]
	v_mfma_i32_16x16x64_i8 v[14:17], v[154:157], v[210:213], v[14:17]
	v_mfma_i32_16x16x64_i8 v[10:13], v[162:165], v[210:213], v[10:13]
	s_setprio 0
	s_setprio 1
	v_mfma_i32_16x16x64_i8 v[54:57], v[166:169], v[182:185], v[54:57]
	v_mfma_i32_16x16x64_i8 v[50:53], v[174:177], v[182:185], v[50:53]
	v_mfma_i32_16x16x64_i8 v[38:41], v[166:169], v[190:193], v[38:41]
	v_mfma_i32_16x16x64_i8 v[34:37], v[174:177], v[190:193], v[34:37]
	v_mfma_i32_16x16x64_i8 v[22:25], v[166:169], v[198:201], v[22:25]
	v_mfma_i32_16x16x64_i8 v[18:21], v[174:177], v[198:201], v[18:21]
	v_mfma_i32_16x16x64_i8 v[6:9], v[166:169], v[206:209], v[6:9]
	v_mfma_i32_16x16x64_i8 v[2:5], v[174:177], v[206:209], v[2:5]
	v_mfma_i32_16x16x64_i8 v[54:57], v[170:173], v[186:189], v[54:57]
	v_mfma_i32_16x16x64_i8 v[50:53], v[178:181], v[186:189], v[50:53]
	v_mfma_i32_16x16x64_i8 v[38:41], v[170:173], v[194:197], v[38:41]
	v_mfma_i32_16x16x64_i8 v[34:37], v[178:181], v[194:197], v[34:37]
	v_mfma_i32_16x16x64_i8 v[22:25], v[170:173], v[202:205], v[22:25]
	v_mfma_i32_16x16x64_i8 v[18:21], v[178:181], v[202:205], v[18:21]
	v_mfma_i32_16x16x64_i8 v[6:9], v[170:173], v[210:213], v[6:9]
	v_mfma_i32_16x16x64_i8 v[2:5], v[178:181], v[210:213], v[2:5]
	s_setprio 0
	s_barrier
	s_add_i32 s65, s65, 2
	s_add_u32 s48, s48, 0x100
	s_addc_u32 s49, s49, 0
	s_add_u32 s25, s25, 0x100
	s_addc_u32 s64, s64, 0
	s_cmp_gt_u32 s65, 5
	s_cbranch_scc0 .LBB0_445
	s_branch .Lpeel_exit_445
	.p2align	6

.LBB0_821:
	s_add_u32 s4, s79, s50
	s_addc_u32 s5, s82, s51
	s_add_u32 s46, s4, 0x9800100
	s_addc_u32 s47, s5, 0
	s_add_u32 s58, s64, s50
	s_addc_u32 s59, s83, s51
	s_add_i32 s85, 0, 0x10000
	s_cmpk_eq_i32 s50, 0x1500
	s_cselect_b32 s47, s49, s47
	s_cselect_b32 s46, s48, s46
	v_add_u32_e32 v0, s85, v134
	s_cselect_b32 s59, s71, s59
	s_cselect_b32 s58, s70, s58
	s_add_i32 s86, 0, 0x14000
	ds_read_b128 v[136:139], v0
	ds_read_b128 v[140:143], v0 offset:1024
	ds_read_b128 v[144:147], v0 offset:2048
	ds_read_b128 v[148:151], v0 offset:3072
	ds_read_b128 v[152:155], v0 offset:16384
	ds_read_b128 v[156:159], v0 offset:17408
	ds_read_b128 v[160:163], v0 offset:18432
	ds_read_b128 v[164:167], v0 offset:19456
	ds_read_b128 v[168:171], v135
	ds_read_b128 v[172:175], v135 offset:1024
	ds_read_b128 v[176:179], v135 offset:2048
	ds_read_b128 v[180:183], v135 offset:3072
	ds_read_b128 v[184:187], v135 offset:4096
	ds_read_b128 v[188:191], v135 offset:5120
	ds_read_b128 v[192:195], v135 offset:6144
	ds_read_b128 v[198:201], v135 offset:7168
	s_add_i32 m0, s60, 0xc000
	s_add_u32 s100, s4, s88
	s_addc_u32 s101, s5, s89
	global_load_lds_dwordx4 v130, s[100:101]
	s_add_i32 m0, s60, 0xe000
	s_nop 0
	global_load_lds_dwordx4 v131, s[100:101]
	s_waitcnt vmcnt(8)
	s_waitcnt lgkmcnt(0)
	s_setprio 1
	s_barrier
	v_mfma_f32_16x16x32_bf16 v[126:129], v[136:139], v[168:171], v[126:129]
	v_mfma_f32_16x16x32_bf16 v[122:125], v[144:147], v[168:171], v[122:125]
	v_mfma_f32_16x16x32_bf16 v[110:113], v[136:139], v[176:179], v[110:113]
	v_mfma_f32_16x16x32_bf16 v[106:109], v[144:147], v[176:179], v[106:109]
	v_mfma_f32_16x16x32_bf16 v[94:97], v[136:139], v[184:187], v[94:97]
	v_mfma_f32_16x16x32_bf16 v[90:93], v[144:147], v[184:187], v[90:93]
	v_mfma_f32_16x16x32_bf16 v[78:81], v[136:139], v[192:195], v[78:81]
	v_mfma_f32_16x16x32_bf16 v[74:77], v[144:147], v[192:195], v[74:77]
	v_mfma_f32_16x16x32_bf16 v[126:129], v[140:143], v[172:175], v[126:129]
	v_mfma_f32_16x16x32_bf16 v[122:125], v[148:151], v[172:175], v[122:125]
	v_mfma_f32_16x16x32_bf16 v[110:113], v[140:143], v[180:183], v[110:113]
	v_mfma_f32_16x16x32_bf16 v[106:109], v[148:151], v[180:183], v[106:109]
	v_mfma_f32_16x16x32_bf16 v[94:97], v[140:143], v[188:191], v[94:97]
	v_mfma_f32_16x16x32_bf16 v[90:93], v[148:151], v[188:191], v[90:93]
	v_mfma_f32_16x16x32_bf16 v[78:81], v[140:143], v[198:201], v[78:81]
	v_mfma_f32_16x16x32_bf16 v[74:77], v[148:151], v[198:201], v[74:77]
	s_setprio 0
	s_setprio 1
	v_mfma_f32_16x16x32_bf16 v[118:121], v[152:155], v[168:171], v[118:121]
	v_mfma_f32_16x16x32_bf16 v[114:117], v[160:163], v[168:171], v[114:117]
	v_mfma_f32_16x16x32_bf16 v[102:105], v[152:155], v[176:179], v[102:105]
	v_mfma_f32_16x16x32_bf16 v[98:101], v[160:163], v[176:179], v[98:101]
	v_mfma_f32_16x16x32_bf16 v[86:89], v[152:155], v[184:187], v[86:89]
	v_mfma_f32_16x16x32_bf16 v[82:85], v[160:163], v[184:187], v[82:85]
	v_mfma_f32_16x16x32_bf16 v[70:73], v[152:155], v[192:195], v[70:73]
	v_mfma_f32_16x16x32_bf16 v[66:69], v[160:163], v[192:195], v[66:69]
	v_mfma_f32_16x16x32_bf16 v[118:121], v[156:159], v[172:175], v[118:121]
	v_mfma_f32_16x16x32_bf16 v[114:117], v[164:167], v[172:175], v[114:117]
	v_mfma_f32_16x16x32_bf16 v[102:105], v[156:159], v[180:183], v[102:105]
	v_mfma_f32_16x16x32_bf16 v[98:101], v[164:167], v[180:183], v[98:101]
	v_mfma_f32_16x16x32_bf16 v[86:89], v[156:159], v[188:191], v[86:89]
	v_mfma_f32_16x16x32_bf16 v[82:85], v[164:167], v[188:191], v[82:85]
	v_mfma_f32_16x16x32_bf16 v[70:73], v[156:159], v[198:201], v[70:73]
	v_mfma_f32_16x16x32_bf16 v[66:69], v[164:167], v[198:201], v[66:69]
	s_setprio 0
	s_barrier
	s_add_i32 s4, s85, s26
	ds_read_b128 v[168:171], v135 offset:16384
	ds_read_b128 v[172:175], v135 offset:17408
	ds_read_b128 v[176:179], v135 offset:18432
	ds_read_b128 v[180:183], v135 offset:19456
	ds_read_b128 v[184:187], v135 offset:20480
	ds_read_b128 v[188:191], v135 offset:21504
	ds_read_b128 v[192:195], v135 offset:22528
	ds_read_b128 v[198:201], v135 offset:23552
	s_mov_b32 m0, s4
	s_nop 0
	global_load_lds_dwordx4 v132, s[58:59]
	s_add_i32 m0, s4, 0x2000
	s_add_u32 s4, s58, 0xb0000
	global_load_lds_dwordx4 v133, s[58:59]
	s_addc_u32 s5, s59, 0
	s_add_i32 s85, s86, s26
	s_mov_b32 m0, s85
	s_nop 0
	global_load_lds_dwordx4 v132, s[4:5]
	s_add_i32 m0, s85, 0x2000
	s_nop 0
	global_load_lds_dwordx4 v133, s[4:5]
	s_mov_b32 m0, s60
	s_nop 0
	global_load_lds_dwordx4 v130, s[46:47]
	s_mov_b32 m0, s65
	s_nop 0
	global_load_lds_dwordx4 v131, s[46:47]
	s_waitcnt vmcnt(8)
	s_waitcnt lgkmcnt(0)
	s_setprio 1
	s_barrier
	v_mfma_f32_16x16x32_bf16 v[62:65], v[136:139], v[168:171], v[62:65]
	v_mfma_f32_16x16x32_bf16 v[58:61], v[144:147], v[168:171], v[58:61]
	v_mfma_f32_16x16x32_bf16 v[46:49], v[136:139], v[176:179], v[46:49]
	v_mfma_f32_16x16x32_bf16 v[42:45], v[144:147], v[176:179], v[42:45]
	v_mfma_f32_16x16x32_bf16 v[30:33], v[136:139], v[184:187], v[30:33]
	v_mfma_f32_16x16x32_bf16 v[26:29], v[144:147], v[184:187], v[26:29]
	v_mfma_f32_16x16x32_bf16 v[14:17], v[136:139], v[192:195], v[14:17]
	v_mfma_f32_16x16x32_bf16 v[10:13], v[144:147], v[192:195], v[10:13]
	v_mfma_f32_16x16x32_bf16 v[62:65], v[140:143], v[172:175], v[62:65]
	v_mfma_f32_16x16x32_bf16 v[58:61], v[148:151], v[172:175], v[58:61]
	v_mfma_f32_16x16x32_bf16 v[46:49], v[140:143], v[180:183], v[46:49]
	v_mfma_f32_16x16x32_bf16 v[42:45], v[148:151], v[180:183], v[42:45]
	v_mfma_f32_16x16x32_bf16 v[30:33], v[140:143], v[188:191], v[30:33]
	v_mfma_f32_16x16x32_bf16 v[26:29], v[148:151], v[188:191], v[26:29]
	v_mfma_f32_16x16x32_bf16 v[14:17], v[140:143], v[198:201], v[14:17]
	v_mfma_f32_16x16x32_bf16 v[10:13], v[148:151], v[198:201], v[10:13]
	s_setprio 0
	s_setprio 1
	v_mfma_f32_16x16x32_bf16 v[54:57], v[152:155], v[168:171], v[54:57]
	v_mfma_f32_16x16x32_bf16 v[50:53], v[160:163], v[168:171], v[50:53]
	v_mfma_f32_16x16x32_bf16 v[38:41], v[152:155], v[176:179], v[38:41]
	v_mfma_f32_16x16x32_bf16 v[34:37], v[160:163], v[176:179], v[34:37]
	v_mfma_f32_16x16x32_bf16 v[22:25], v[152:155], v[184:187], v[22:25]
	v_mfma_f32_16x16x32_bf16 v[18:21], v[160:163], v[184:187], v[18:21]
	v_mfma_f32_16x16x32_bf16 v[6:9], v[152:155], v[192:195], v[6:9]
	v_mfma_f32_16x16x32_bf16 v[2:5], v[160:163], v[192:195], v[2:5]
	v_mfma_f32_16x16x32_bf16 v[54:57], v[156:159], v[172:175], v[54:57]
	v_mfma_f32_16x16x32_bf16 v[50:53], v[164:167], v[172:175], v[50:53]
	v_mfma_f32_16x16x32_bf16 v[38:41], v[156:159], v[180:183], v[38:41]
	v_mfma_f32_16x16x32_bf16 v[34:37], v[164:167], v[180:183], v[34:37]
	v_mfma_f32_16x16x32_bf16 v[22:25], v[156:159], v[188:191], v[22:25]
	v_mfma_f32_16x16x32_bf16 v[18:21], v[164:167], v[188:191], v[18:21]
	v_mfma_f32_16x16x32_bf16 v[6:9], v[156:159], v[198:201], v[6:9]
	v_mfma_f32_16x16x32_bf16 v[2:5], v[164:167], v[198:201], v[2:5]
	s_setprio 0
	s_barrier
	s_add_i32 s85, 0, 0x18000
	s_add_i32 s86, 0, 0x1c000
	ds_read_b128 v[136:139], v0 offset:32768
	ds_read_b128 v[140:143], v0 offset:33792
	ds_read_b128 v[144:147], v0 offset:34816
	ds_read_b128 v[148:151], v0 offset:35840
	ds_read_b128 v[152:155], v0 offset:49152
	ds_read_b128 v[156:159], v0 offset:50176
	ds_read_b128 v[160:163], v0 offset:51200
	ds_read_b128 v[164:167], v0 offset:52224
	s_add_u32 s4, s46, 0xb0000
	s_mov_b32 m0, s68
	ds_read_b128 v[168:171], v135 offset:32768
	ds_read_b128 v[172:175], v135 offset:33792
	ds_read_b128 v[176:179], v135 offset:34816
	ds_read_b128 v[180:183], v135 offset:35840
	ds_read_b128 v[184:187], v135 offset:36864
	ds_read_b128 v[188:191], v135 offset:37888
	ds_read_b128 v[192:195], v135 offset:38912
	ds_read_b128 v[198:201], v135 offset:39936
	s_addc_u32 s5, s47, 0
	s_nop 0
	global_load_lds_dwordx4 v130, s[4:5]
	s_mov_b32 m0, s69
	s_nop 0
	global_load_lds_dwordx4 v131, s[4:5]
	s_waitcnt vmcnt(8)
	s_waitcnt lgkmcnt(0)
	s_setprio 1
	s_barrier
	v_mfma_f32_16x16x32_bf16 v[126:129], v[136:139], v[168:171], v[126:129]
	v_mfma_f32_16x16x32_bf16 v[122:125], v[144:147], v[168:171], v[122:125]
	v_mfma_f32_16x16x32_bf16 v[110:113], v[136:139], v[176:179], v[110:113]
	v_mfma_f32_16x16x32_bf16 v[106:109], v[144:147], v[176:179], v[106:109]
	v_mfma_f32_16x16x32_bf16 v[94:97], v[136:139], v[184:187], v[94:97]
	v_mfma_f32_16x16x32_bf16 v[90:93], v[144:147], v[184:187], v[90:93]
	v_mfma_f32_16x16x32_bf16 v[78:81], v[136:139], v[192:195], v[78:81]
	v_mfma_f32_16x16x32_bf16 v[74:77], v[144:147], v[192:195], v[74:77]
	v_mfma_f32_16x16x32_bf16 v[126:129], v[140:143], v[172:175], v[126:129]
	v_mfma_f32_16x16x32_bf16 v[122:125], v[148:151], v[172:175], v[122:125]
	v_mfma_f32_16x16x32_bf16 v[110:113], v[140:143], v[180:183], v[110:113]
	v_mfma_f32_16x16x32_bf16 v[106:109], v[148:151], v[180:183], v[106:109]
	v_mfma_f32_16x16x32_bf16 v[94:97], v[140:143], v[188:191], v[94:97]
	v_mfma_f32_16x16x32_bf16 v[90:93], v[148:151], v[188:191], v[90:93]
	v_mfma_f32_16x16x32_bf16 v[78:81], v[140:143], v[198:201], v[78:81]
	v_mfma_f32_16x16x32_bf16 v[74:77], v[148:151], v[198:201], v[74:77]
	s_setprio 0
	s_setprio 1
	v_mfma_f32_16x16x32_bf16 v[118:121], v[152:155], v[168:171], v[118:121]
	v_mfma_f32_16x16x32_bf16 v[114:117], v[160:163], v[168:171], v[114:117]
	v_mfma_f32_16x16x32_bf16 v[102:105], v[152:155], v[176:179], v[102:105]
	v_mfma_f32_16x16x32_bf16 v[98:101], v[160:163], v[176:179], v[98:101]
	v_mfma_f32_16x16x32_bf16 v[86:89], v[152:155], v[184:187], v[86:89]
	v_mfma_f32_16x16x32_bf16 v[82:85], v[160:163], v[184:187], v[82:85]
	v_mfma_f32_16x16x32_bf16 v[70:73], v[152:155], v[192:195], v[70:73]
	v_mfma_f32_16x16x32_bf16 v[66:69], v[160:163], v[192:195], v[66:69]
	v_mfma_f32_16x16x32_bf16 v[118:121], v[156:159], v[172:175], v[118:121]
	v_mfma_f32_16x16x32_bf16 v[114:117], v[164:167], v[172:175], v[114:117]
	v_mfma_f32_16x16x32_bf16 v[102:105], v[156:159], v[180:183], v[102:105]
	v_mfma_f32_16x16x32_bf16 v[98:101], v[164:167], v[180:183], v[98:101]
	v_mfma_f32_16x16x32_bf16 v[86:89], v[156:159], v[188:191], v[86:89]
	v_mfma_f32_16x16x32_bf16 v[82:85], v[164:167], v[188:191], v[82:85]
	v_mfma_f32_16x16x32_bf16 v[70:73], v[156:159], v[198:201], v[70:73]
	v_mfma_f32_16x16x32_bf16 v[66:69], v[164:167], v[198:201], v[66:69]
	s_setprio 0
	s_barrier
	ds_read_b128 v[168:171], v135 offset:49152
	ds_read_b128 v[172:175], v135 offset:50176
	ds_read_b128 v[176:179], v135 offset:51200
	ds_read_b128 v[180:183], v135 offset:52224
	ds_read_b128 v[184:187], v135 offset:53248
	ds_read_b128 v[188:191], v135 offset:54272
	ds_read_b128 v[192:195], v135 offset:55296
	ds_read_b128 v[198:201], v135 offset:56320
	s_add_i32 s4, s85, s26
	s_add_u32 s100, s58, s38
	s_addc_u32 s101, s59, s39
	s_mov_b32 m0, s4
	s_nop 0
	global_load_lds_dwordx4 v132, s[100:101]
	s_add_i32 m0, s4, 0x2000
	s_add_u32 s4, s58, 0xb0080
	s_addc_u32 s5, s59, 0
	s_add_i32 s58, s86, s26
	global_load_lds_dwordx4 v133, s[100:101]
	s_mov_b32 m0, s58
	s_nop 0
	global_load_lds_dwordx4 v132, s[4:5]
	s_add_i32 m0, s58, 0x2000
	s_nop 0
	global_load_lds_dwordx4 v133, s[4:5]
	s_mov_b32 m0, s75
	s_add_u32 s100, s46, s38
	s_addc_u32 s101, s47, s39
	v_mov_b32_e32 v0, v131
	global_load_lds_dwordx4 v130, s[100:101]
	s_mov_b32 m0, s78
	s_nop 0
	global_load_lds_dwordx4 v131, s[100:101]
	s_waitcnt vmcnt(8)
	s_waitcnt lgkmcnt(0)
	s_setprio 1
	s_barrier
	v_mfma_f32_16x16x32_bf16 v[62:65], v[136:139], v[168:171], v[62:65]
	v_mfma_f32_16x16x32_bf16 v[58:61], v[144:147], v[168:171], v[58:61]
	v_mfma_f32_16x16x32_bf16 v[46:49], v[136:139], v[176:179], v[46:49]
	v_mfma_f32_16x16x32_bf16 v[42:45], v[144:147], v[176:179], v[42:45]
	v_mfma_f32_16x16x32_bf16 v[30:33], v[136:139], v[184:187], v[30:33]
	v_mfma_f32_16x16x32_bf16 v[26:29], v[144:147], v[184:187], v[26:29]
	v_mfma_f32_16x16x32_bf16 v[14:17], v[136:139], v[192:195], v[14:17]
	v_mfma_f32_16x16x32_bf16 v[10:13], v[144:147], v[192:195], v[10:13]
	v_mfma_f32_16x16x32_bf16 v[62:65], v[140:143], v[172:175], v[62:65]
	v_mfma_f32_16x16x32_bf16 v[58:61], v[148:151], v[172:175], v[58:61]
	v_mfma_f32_16x16x32_bf16 v[46:49], v[140:143], v[180:183], v[46:49]
	v_mfma_f32_16x16x32_bf16 v[42:45], v[148:151], v[180:183], v[42:45]
	v_mfma_f32_16x16x32_bf16 v[30:33], v[140:143], v[188:191], v[30:33]
	v_mfma_f32_16x16x32_bf16 v[26:29], v[148:151], v[188:191], v[26:29]
	v_mfma_f32_16x16x32_bf16 v[14:17], v[140:143], v[198:201], v[14:17]
	v_mfma_f32_16x16x32_bf16 v[10:13], v[148:151], v[198:201], v[10:13]
	s_setprio 0
	s_setprio 1
	v_mfma_f32_16x16x32_bf16 v[54:57], v[152:155], v[168:171], v[54:57]
	v_mfma_f32_16x16x32_bf16 v[50:53], v[160:163], v[168:171], v[50:53]
	v_mfma_f32_16x16x32_bf16 v[38:41], v[152:155], v[176:179], v[38:41]
	v_mfma_f32_16x16x32_bf16 v[34:37], v[160:163], v[176:179], v[34:37]
	v_mfma_f32_16x16x32_bf16 v[22:25], v[152:155], v[184:187], v[22:25]
	v_mfma_f32_16x16x32_bf16 v[18:21], v[160:163], v[184:187], v[18:21]
	v_mfma_f32_16x16x32_bf16 v[6:9], v[152:155], v[192:195], v[6:9]
	v_mfma_f32_16x16x32_bf16 v[2:5], v[160:163], v[192:195], v[2:5]
	v_mfma_f32_16x16x32_bf16 v[54:57], v[156:159], v[172:175], v[54:57]
	v_mfma_f32_16x16x32_bf16 v[50:53], v[164:167], v[172:175], v[50:53]
	v_mfma_f32_16x16x32_bf16 v[38:41], v[156:159], v[180:183], v[38:41]
	v_mfma_f32_16x16x32_bf16 v[34:37], v[164:167], v[180:183], v[34:37]
	v_mfma_f32_16x16x32_bf16 v[22:25], v[156:159], v[188:191], v[22:25]
	v_mfma_f32_16x16x32_bf16 v[18:21], v[164:167], v[188:191], v[18:21]
	v_mfma_f32_16x16x32_bf16 v[6:9], v[156:159], v[198:201], v[6:9]
	v_mfma_f32_16x16x32_bf16 v[2:5], v[164:167], v[198:201], v[2:5]
	s_setprio 0
	s_barrier
	s_add_i32 s84, s84, 2
	s_add_u32 s50, s50, 0x100
	s_addc_u32 s51, s51, 0
	s_cmp_gt_u32 s84, 41
	s_cbranch_scc0 .LBB0_821

.LBB0_843:
	s_or_b64 exec, exec, s[42:43]
	s_waitcnt lgkmcnt(0)
	s_mov_b32 s4, s100
	s_nop 0
	v_add_u32_e32 v0, s4, v0
	v_and_b32_e32 v2, 3, v0
	v_cmp_ne_u32_e32 vcc, 3, v2
	s_and_saveexec_b64 s[40:41], vcc
	s_cbranch_execz .LBB0_858
	s_load_dword s100, s[24:25], 0x0 glc
	v_bitop3_b32 v0, v0, -4, v0 bitop3:0xc
	s_waitcnt lgkmcnt(0)
	v_add_u32_e32 v2, s100, v0
	v_cmp_gt_i32_e32 vcc, 0, v2
	s_and_b64 exec, exec, vcc
	s_cbranch_execz .LBB0_858
	s_add_u32 s22, s22, 0x4200
	s_addc_u32 s23, s23, 0
	s_mov_b32 s4, 1
	s_mov_b64 s[42:43], 0
	s_branch .LBB0_847

.LBB0_869:
	s_add_u32 s4, s10, s2
	s_addc_u32 s5, s11, s3
	s_add_u32 s22, s4, 0x100
	s_addc_u32 s23, s5, 0
	s_add_u32 s46, s58, s2
	s_addc_u32 s47, s59, s3
	s_add_i32 s69, 0, 0x10000
	s_cmp_eq_u32 s68, 40
	s_cselect_b32 s23, s11, s23
	s_cselect_b32 s22, s10, s22
	v_add_u32_e32 v0, s69, v126
	s_cselect_b32 s47, s17, s47
	s_cselect_b32 s46, s16, s46
	s_add_i32 s70, 0, 0x14000
	ds_read_b128 v[128:131], v0
	ds_read_b128 v[142:145], v0 offset:1024
	ds_read_b128 v[146:149], v0 offset:2048
	ds_read_b128 v[150:153], v0 offset:3072
	ds_read_b128 v[154:157], v0 offset:16384
	ds_read_b128 v[160:163], v0 offset:17408
	ds_read_b128 v[164:167], v0 offset:18432
	ds_read_b128 v[168:171], v0 offset:19456
	ds_read_b128 v[172:175], v127
	ds_read_b128 v[176:179], v127 offset:1024
	ds_read_b128 v[180:183], v127 offset:2048
	ds_read_b128 v[184:187], v127 offset:3072
	ds_read_b128 v[188:191], v127 offset:4096
	ds_read_b128 v[192:195], v127 offset:5120
	ds_read_b128 v[196:199], v127 offset:6144
	ds_read_b128 v[200:203], v127 offset:7168
	s_add_i32 m0, s41, 0xc000
	s_add_u32 s100, s4, s62
	s_addc_u32 s101, s5, s63
	global_load_lds_dwordx4 v122, s[100:101]
	s_add_i32 m0, s41, 0xe000
	s_nop 0
	global_load_lds_dwordx4 v123, s[100:101]
	s_waitcnt vmcnt(8)
	s_waitcnt lgkmcnt(0)
	s_setprio 1
	s_barrier
	v_mfma_f32_16x16x32_bf16 v[138:141], v[128:131], v[172:175], v[138:141]
	v_mfma_f32_16x16x32_bf16 v[132:135], v[146:149], v[172:175], v[134:137]
	v_mfma_f32_16x16x32_bf16 v[110:113], v[128:131], v[180:183], v[110:113]
	v_mfma_f32_16x16x32_bf16 v[106:109], v[146:149], v[180:183], v[106:109]
	v_mfma_f32_16x16x32_bf16 v[94:97], v[128:131], v[188:191], v[94:97]
	v_mfma_f32_16x16x32_bf16 v[90:93], v[146:149], v[188:191], v[90:93]
	v_mfma_f32_16x16x32_bf16 v[78:81], v[128:131], v[196:199], v[78:81]
	v_mfma_f32_16x16x32_bf16 v[74:77], v[146:149], v[196:199], v[74:77]
	v_mfma_f32_16x16x32_bf16 v[138:141], v[142:145], v[176:179], v[138:141]
	v_mfma_f32_16x16x32_bf16 v[132:135], v[150:153], v[176:179], v[132:135]
	v_mfma_f32_16x16x32_bf16 v[110:113], v[142:145], v[184:187], v[110:113]
	v_mfma_f32_16x16x32_bf16 v[106:109], v[150:153], v[184:187], v[106:109]
	v_mfma_f32_16x16x32_bf16 v[94:97], v[142:145], v[192:195], v[94:97]
	v_mfma_f32_16x16x32_bf16 v[90:93], v[150:153], v[192:195], v[90:93]
	v_mfma_f32_16x16x32_bf16 v[78:81], v[142:145], v[200:203], v[78:81]
	v_mfma_f32_16x16x32_bf16 v[74:77], v[150:153], v[200:203], v[74:77]
	s_setprio 0
	s_setprio 1
	v_mfma_f32_16x16x32_bf16 v[118:121], v[154:157], v[172:175], v[118:121]
	v_mfma_f32_16x16x32_bf16 v[114:117], v[164:167], v[172:175], v[114:117]
	v_mfma_f32_16x16x32_bf16 v[102:105], v[154:157], v[180:183], v[102:105]
	v_mfma_f32_16x16x32_bf16 v[98:101], v[164:167], v[180:183], v[98:101]
	v_mfma_f32_16x16x32_bf16 v[86:89], v[154:157], v[188:191], v[86:89]
	v_mfma_f32_16x16x32_bf16 v[82:85], v[164:167], v[188:191], v[82:85]
	v_mfma_f32_16x16x32_bf16 v[70:73], v[154:157], v[196:199], v[70:73]
	v_mfma_f32_16x16x32_bf16 v[66:69], v[164:167], v[196:199], v[66:69]
	v_mfma_f32_16x16x32_bf16 v[118:121], v[160:163], v[176:179], v[118:121]
	v_mfma_f32_16x16x32_bf16 v[114:117], v[168:171], v[176:179], v[114:117]
	v_mfma_f32_16x16x32_bf16 v[102:105], v[160:163], v[184:187], v[102:105]
	v_mfma_f32_16x16x32_bf16 v[98:101], v[168:171], v[184:187], v[98:101]
	v_mfma_f32_16x16x32_bf16 v[86:89], v[160:163], v[192:195], v[86:89]
	v_mfma_f32_16x16x32_bf16 v[82:85], v[168:171], v[192:195], v[82:85]
	v_mfma_f32_16x16x32_bf16 v[70:73], v[160:163], v[200:203], v[70:73]
	v_mfma_f32_16x16x32_bf16 v[66:69], v[168:171], v[200:203], v[66:69]
	s_setprio 0
	s_barrier
	s_add_i32 s4, s69, s26
	ds_read_b128 v[172:175], v127 offset:16384
	ds_read_b128 v[176:179], v127 offset:17408
	ds_read_b128 v[180:183], v127 offset:18432
	ds_read_b128 v[184:187], v127 offset:19456
	ds_read_b128 v[188:191], v127 offset:20480
	ds_read_b128 v[192:195], v127 offset:21504
	ds_read_b128 v[196:199], v127 offset:22528
	ds_read_b128 v[200:203], v127 offset:23552
	s_mov_b32 m0, s4
	s_nop 0
	global_load_lds_dwordx4 v124, s[46:47]
	s_add_i32 m0, s4, 0x2000
	s_add_u32 s4, s46, 0xb0000
	global_load_lds_dwordx4 v125, s[46:47]
	s_addc_u32 s5, s47, 0
	s_add_i32 s69, s70, s26
	s_mov_b32 m0, s69
	s_nop 0
	global_load_lds_dwordx4 v124, s[4:5]
	s_add_i32 m0, s69, 0x2000
	s_nop 0
	global_load_lds_dwordx4 v125, s[4:5]
	s_mov_b32 m0, s41
	s_nop 0
	global_load_lds_dwordx4 v122, s[22:23]
	s_mov_b32 m0, s48
	s_nop 0
	global_load_lds_dwordx4 v123, s[22:23]
	s_waitcnt vmcnt(8)
	s_waitcnt lgkmcnt(0)
	s_setprio 1
	s_barrier
	v_mfma_f32_16x16x32_bf16 v[62:65], v[128:131], v[172:175], v[62:65]
	v_mfma_f32_16x16x32_bf16 v[58:61], v[146:149], v[172:175], v[58:61]
	v_mfma_f32_16x16x32_bf16 v[46:49], v[128:131], v[180:183], v[46:49]
	v_mfma_f32_16x16x32_bf16 v[42:45], v[146:149], v[180:183], v[42:45]
	v_mfma_f32_16x16x32_bf16 v[30:33], v[128:131], v[188:191], v[30:33]
	v_mfma_f32_16x16x32_bf16 v[26:29], v[146:149], v[188:191], v[26:29]
	v_mfma_f32_16x16x32_bf16 v[14:17], v[128:131], v[196:199], v[14:17]
	v_mfma_f32_16x16x32_bf16 v[10:13], v[146:149], v[196:199], v[10:13]
	v_mfma_f32_16x16x32_bf16 v[62:65], v[142:145], v[176:179], v[62:65]
	v_mfma_f32_16x16x32_bf16 v[58:61], v[150:153], v[176:179], v[58:61]
	v_mfma_f32_16x16x32_bf16 v[46:49], v[142:145], v[184:187], v[46:49]
	v_mfma_f32_16x16x32_bf16 v[42:45], v[150:153], v[184:187], v[42:45]
	v_mfma_f32_16x16x32_bf16 v[30:33], v[142:145], v[192:195], v[30:33]
	v_mfma_f32_16x16x32_bf16 v[26:29], v[150:153], v[192:195], v[26:29]
	v_mfma_f32_16x16x32_bf16 v[14:17], v[142:145], v[200:203], v[14:17]
	v_mfma_f32_16x16x32_bf16 v[10:13], v[150:153], v[200:203], v[10:13]
	s_setprio 0
	s_setprio 1
	v_mfma_f32_16x16x32_bf16 v[54:57], v[154:157], v[172:175], v[54:57]
	v_mfma_f32_16x16x32_bf16 v[50:53], v[164:167], v[172:175], v[50:53]
	v_mfma_f32_16x16x32_bf16 v[38:41], v[154:157], v[180:183], v[38:41]
	v_mfma_f32_16x16x32_bf16 v[34:37], v[164:167], v[180:183], v[34:37]
	v_mfma_f32_16x16x32_bf16 v[22:25], v[154:157], v[188:191], v[22:25]
	v_mfma_f32_16x16x32_bf16 v[18:21], v[164:167], v[188:191], v[18:21]
	v_mfma_f32_16x16x32_bf16 v[6:9], v[154:157], v[196:199], v[6:9]
	v_mfma_f32_16x16x32_bf16 v[2:5], v[164:167], v[196:199], v[2:5]
	v_mfma_f32_16x16x32_bf16 v[54:57], v[160:163], v[176:179], v[54:57]
	v_mfma_f32_16x16x32_bf16 v[50:53], v[168:171], v[176:179], v[50:53]
	v_mfma_f32_16x16x32_bf16 v[38:41], v[160:163], v[184:187], v[38:41]
	v_mfma_f32_16x16x32_bf16 v[34:37], v[168:171], v[184:187], v[34:37]
	v_mfma_f32_16x16x32_bf16 v[22:25], v[160:163], v[192:195], v[22:25]
	v_mfma_f32_16x16x32_bf16 v[18:21], v[168:171], v[192:195], v[18:21]
	v_mfma_f32_16x16x32_bf16 v[6:9], v[160:163], v[200:203], v[6:9]
	v_mfma_f32_16x16x32_bf16 v[2:5], v[168:171], v[200:203], v[2:5]
	s_setprio 0
	s_barrier
	s_add_i32 s69, 0, 0x18000
	s_add_i32 s70, 0, 0x1c000
	ds_read_b128 v[128:131], v0 offset:32768
	ds_read_b128 v[142:145], v0 offset:33792
	ds_read_b128 v[146:149], v0 offset:34816
	ds_read_b128 v[150:153], v0 offset:35840
	ds_read_b128 v[154:157], v0 offset:49152
	ds_read_b128 v[160:163], v0 offset:50176
	ds_read_b128 v[164:167], v0 offset:51200
	ds_read_b128 v[168:171], v0 offset:52224
	s_add_u32 s4, s22, 0xb0000
	s_mov_b32 m0, s49
	ds_read_b128 v[172:175], v127 offset:32768
	ds_read_b128 v[176:179], v127 offset:33792
	ds_read_b128 v[180:183], v127 offset:34816
	ds_read_b128 v[184:187], v127 offset:35840
	ds_read_b128 v[188:191], v127 offset:36864
	ds_read_b128 v[192:195], v127 offset:37888
	ds_read_b128 v[196:199], v127 offset:38912
	ds_read_b128 v[200:203], v127 offset:39936
	s_addc_u32 s5, s23, 0
	s_nop 0
	global_load_lds_dwordx4 v122, s[4:5]
	s_mov_b32 m0, s50
	s_nop 0
	global_load_lds_dwordx4 v123, s[4:5]
	s_waitcnt vmcnt(8)
	s_waitcnt lgkmcnt(0)
	s_setprio 1
	s_barrier
	v_mfma_f32_16x16x32_bf16 v[136:139], v[128:131], v[172:175], v[138:141]
	v_mfma_f32_16x16x32_bf16 v[132:135], v[146:149], v[172:175], v[132:135]
	v_mfma_f32_16x16x32_bf16 v[110:113], v[128:131], v[180:183], v[110:113]
	v_mfma_f32_16x16x32_bf16 v[106:109], v[146:149], v[180:183], v[106:109]
	v_mfma_f32_16x16x32_bf16 v[94:97], v[128:131], v[188:191], v[94:97]
	v_mfma_f32_16x16x32_bf16 v[90:93], v[146:149], v[188:191], v[90:93]
	v_mfma_f32_16x16x32_bf16 v[78:81], v[128:131], v[196:199], v[78:81]
	v_mfma_f32_16x16x32_bf16 v[74:77], v[146:149], v[196:199], v[74:77]
	v_mfma_f32_16x16x32_bf16 v[138:141], v[142:145], v[176:179], v[136:139]
	v_mfma_f32_16x16x32_bf16 v[134:137], v[150:153], v[176:179], v[132:135]
	v_mfma_f32_16x16x32_bf16 v[110:113], v[142:145], v[184:187], v[110:113]
	v_mfma_f32_16x16x32_bf16 v[106:109], v[150:153], v[184:187], v[106:109]
	v_mfma_f32_16x16x32_bf16 v[94:97], v[142:145], v[192:195], v[94:97]
	v_mfma_f32_16x16x32_bf16 v[90:93], v[150:153], v[192:195], v[90:93]
	v_mfma_f32_16x16x32_bf16 v[78:81], v[142:145], v[200:203], v[78:81]
	v_mfma_f32_16x16x32_bf16 v[74:77], v[150:153], v[200:203], v[74:77]
	s_setprio 0
	s_setprio 1
	v_mfma_f32_16x16x32_bf16 v[118:121], v[154:157], v[172:175], v[118:121]
	v_mfma_f32_16x16x32_bf16 v[114:117], v[164:167], v[172:175], v[114:117]
	v_mfma_f32_16x16x32_bf16 v[102:105], v[154:157], v[180:183], v[102:105]
	v_mfma_f32_16x16x32_bf16 v[98:101], v[164:167], v[180:183], v[98:101]
	v_mfma_f32_16x16x32_bf16 v[86:89], v[154:157], v[188:191], v[86:89]
	v_mfma_f32_16x16x32_bf16 v[82:85], v[164:167], v[188:191], v[82:85]
	v_mfma_f32_16x16x32_bf16 v[70:73], v[154:157], v[196:199], v[70:73]
	v_mfma_f32_16x16x32_bf16 v[66:69], v[164:167], v[196:199], v[66:69]
	v_mfma_f32_16x16x32_bf16 v[118:121], v[160:163], v[176:179], v[118:121]
	v_mfma_f32_16x16x32_bf16 v[114:117], v[168:171], v[176:179], v[114:117]
	v_mfma_f32_16x16x32_bf16 v[102:105], v[160:163], v[184:187], v[102:105]
	v_mfma_f32_16x16x32_bf16 v[98:101], v[168:171], v[184:187], v[98:101]
	v_mfma_f32_16x16x32_bf16 v[86:89], v[160:163], v[192:195], v[86:89]
	v_mfma_f32_16x16x32_bf16 v[82:85], v[168:171], v[192:195], v[82:85]
	v_mfma_f32_16x16x32_bf16 v[70:73], v[160:163], v[200:203], v[70:73]
	v_mfma_f32_16x16x32_bf16 v[66:69], v[168:171], v[200:203], v[66:69]
	s_setprio 0
	s_barrier
	ds_read_b128 v[172:175], v127 offset:49152
	ds_read_b128 v[176:179], v127 offset:50176
	ds_read_b128 v[180:183], v127 offset:51200
	ds_read_b128 v[184:187], v127 offset:52224
	ds_read_b128 v[188:191], v127 offset:53248
	ds_read_b128 v[192:195], v127 offset:54272
	ds_read_b128 v[196:199], v127 offset:55296
	ds_read_b128 v[200:203], v127 offset:56320
	s_add_i32 s4, s69, s26
	s_add_u32 s100, s46, s38
	s_addc_u32 s101, s47, s39
	s_mov_b32 m0, s4
	s_nop 0
	global_load_lds_dwordx4 v124, s[100:101]
	s_add_i32 m0, s4, 0x2000
	s_add_u32 s4, s46, 0xb0080
	s_addc_u32 s5, s47, 0
	s_add_i32 s46, s70, s26
	global_load_lds_dwordx4 v125, s[100:101]
	s_mov_b32 m0, s46
	s_nop 0
	global_load_lds_dwordx4 v124, s[4:5]
	s_add_i32 m0, s46, 0x2000
	s_nop 0
	global_load_lds_dwordx4 v125, s[4:5]
	s_mov_b32 m0, s64
	s_add_u32 s100, s22, s38
	s_addc_u32 s101, s23, s39
	v_mov_b32_e32 v0, v123
	global_load_lds_dwordx4 v122, s[100:101]
	s_mov_b32 m0, s65
	s_nop 0
	global_load_lds_dwordx4 v123, s[100:101]
	s_waitcnt vmcnt(8)
	s_waitcnt lgkmcnt(0)
	s_setprio 1
	s_barrier
	v_mfma_f32_16x16x32_bf16 v[62:65], v[128:131], v[172:175], v[62:65]
	v_mfma_f32_16x16x32_bf16 v[58:61], v[146:149], v[172:175], v[58:61]
	v_mfma_f32_16x16x32_bf16 v[46:49], v[128:131], v[180:183], v[46:49]
	v_mfma_f32_16x16x32_bf16 v[42:45], v[146:149], v[180:183], v[42:45]
	v_mfma_f32_16x16x32_bf16 v[30:33], v[128:131], v[188:191], v[30:33]
	v_mfma_f32_16x16x32_bf16 v[26:29], v[146:149], v[188:191], v[26:29]
	v_mfma_f32_16x16x32_bf16 v[14:17], v[128:131], v[196:199], v[14:17]
	v_mfma_f32_16x16x32_bf16 v[10:13], v[146:149], v[196:199], v[10:13]
	v_mfma_f32_16x16x32_bf16 v[62:65], v[142:145], v[176:179], v[62:65]
	v_mfma_f32_16x16x32_bf16 v[58:61], v[150:153], v[176:179], v[58:61]
	v_mfma_f32_16x16x32_bf16 v[46:49], v[142:145], v[184:187], v[46:49]
	v_mfma_f32_16x16x32_bf16 v[42:45], v[150:153], v[184:187], v[42:45]
	v_mfma_f32_16x16x32_bf16 v[30:33], v[142:145], v[192:195], v[30:33]
	v_mfma_f32_16x16x32_bf16 v[26:29], v[150:153], v[192:195], v[26:29]
	v_mfma_f32_16x16x32_bf16 v[14:17], v[142:145], v[200:203], v[14:17]
	v_mfma_f32_16x16x32_bf16 v[10:13], v[150:153], v[200:203], v[10:13]
	s_setprio 0
	s_setprio 1
	v_mfma_f32_16x16x32_bf16 v[54:57], v[154:157], v[172:175], v[54:57]
	v_mfma_f32_16x16x32_bf16 v[50:53], v[164:167], v[172:175], v[50:53]
	v_mfma_f32_16x16x32_bf16 v[38:41], v[154:157], v[180:183], v[38:41]
	v_mfma_f32_16x16x32_bf16 v[34:37], v[164:167], v[180:183], v[34:37]
	v_mfma_f32_16x16x32_bf16 v[22:25], v[154:157], v[188:191], v[22:25]
	v_mfma_f32_16x16x32_bf16 v[18:21], v[164:167], v[188:191], v[18:21]
	v_mfma_f32_16x16x32_bf16 v[6:9], v[154:157], v[196:199], v[6:9]
	v_mfma_f32_16x16x32_bf16 v[2:5], v[164:167], v[196:199], v[2:5]
	v_mfma_f32_16x16x32_bf16 v[54:57], v[160:163], v[176:179], v[54:57]
	v_mfma_f32_16x16x32_bf16 v[50:53], v[168:171], v[176:179], v[50:53]
	v_mfma_f32_16x16x32_bf16 v[38:41], v[160:163], v[184:187], v[38:41]
	v_mfma_f32_16x16x32_bf16 v[34:37], v[168:171], v[184:187], v[34:37]
	v_mfma_f32_16x16x32_bf16 v[22:25], v[160:163], v[192:195], v[22:25]
	v_mfma_f32_16x16x32_bf16 v[18:21], v[168:171], v[192:195], v[18:21]
	v_mfma_f32_16x16x32_bf16 v[6:9], v[160:163], v[200:203], v[6:9]
	v_mfma_f32_16x16x32_bf16 v[2:5], v[168:171], v[200:203], v[2:5]
	s_setprio 0
	s_barrier
	s_add_i32 s68, s68, 2
	s_add_u32 s2, s2, 0x100
	s_addc_u32 s3, s3, 0
	s_cmp_gt_u32 s68, 41
	s_cbranch_scc0 .LBB0_869

.LBB0_891:
	s_or_b64 exec, exec, s[42:43]
	s_waitcnt lgkmcnt(0)
	s_mov_b32 s4, s100
	s_nop 0
	v_add_u32_e32 v0, s4, v0
	v_and_b32_e32 v2, 3, v0
	v_cmp_ne_u32_e32 vcc, 3, v2
	s_and_saveexec_b64 s[40:41], vcc
	s_cbranch_execz .LBB0_906
	s_load_dword s100, s[24:25], 0x0 glc
	v_bitop3_b32 v0, v0, -4, v0 bitop3:0xc
	s_waitcnt lgkmcnt(0)
	v_add_u32_e32 v2, s100, v0
	v_cmp_gt_i32_e32 vcc, 0, v2
	s_and_b64 exec, exec, vcc
	s_cbranch_execz .LBB0_906
	s_add_u32 s6, s6, 0x4200
	s_addc_u32 s7, s7, 0
	s_mov_b32 s4, 1
	s_mov_b64 s[42:43], 0
	s_branch .LBB0_895

.LBB0_953:
	s_add_u32 s58, s4, s2
	s_addc_u32 s59, s5, s3
	s_add_u32 s14, s58, 0x100
	s_addc_u32 s15, s59, 0
	s_add_u32 s16, s43, s2
	s_addc_u32 s17, s46, s3
	s_add_i32 s51, 0, 0x10000
	s_cmp_eq_u32 s50, 40
	s_cselect_b32 s15, s5, s15
	s_cselect_b32 s14, s4, s14
	v_add_u32_e32 v0, s51, v135
	s_cselect_b32 s17, s7, s17
	s_cselect_b32 s16, s6, s16
	s_add_i32 s60, 0, 0x14000
	ds_read_b128 v[138:141], v0
	ds_read_b128 v[142:145], v0 offset:1024
	ds_read_b128 v[146:149], v0 offset:2048
	ds_read_b128 v[150:153], v0 offset:3072
	ds_read_b128 v[154:157], v0 offset:16384
	ds_read_b128 v[158:161], v0 offset:17408
	ds_read_b128 v[162:165], v0 offset:18432
	ds_read_b128 v[166:169], v0 offset:19456
	ds_read_b128 v[170:173], v136
	ds_read_b128 v[174:177], v136 offset:1024
	ds_read_b128 v[178:181], v136 offset:2048
	ds_read_b128 v[182:185], v136 offset:3072
	ds_read_b128 v[186:189], v136 offset:4096
	ds_read_b128 v[190:193], v136 offset:5120
	ds_read_b128 v[194:197], v136 offset:6144
	ds_read_b128 v[198:201], v136 offset:7168
	s_add_i32 m0, s37, 0xc000
	s_add_u32 s100, s58, s62
	s_addc_u32 s101, s59, s63
	global_load_lds_dwordx4 v130, s[100:101]
	s_add_i32 m0, s37, 0xe000
	s_nop 0
	global_load_lds_dwordx4 v131, s[100:101]
	s_waitcnt vmcnt(8)
	s_waitcnt lgkmcnt(0)
	s_setprio 1
	s_barrier
	v_mfma_f32_16x16x32_bf16 v[126:129], v[138:141], v[170:173], v[126:129]
	v_mfma_f32_16x16x32_bf16 v[122:125], v[146:149], v[170:173], v[122:125]
	v_mfma_f32_16x16x32_bf16 v[110:113], v[138:141], v[178:181], v[110:113]
	v_mfma_f32_16x16x32_bf16 v[106:109], v[146:149], v[178:181], v[106:109]
	v_mfma_f32_16x16x32_bf16 v[94:97], v[138:141], v[186:189], v[94:97]
	v_mfma_f32_16x16x32_bf16 v[90:93], v[146:149], v[186:189], v[90:93]
	v_mfma_f32_16x16x32_bf16 v[78:81], v[138:141], v[194:197], v[78:81]
	v_mfma_f32_16x16x32_bf16 v[74:77], v[146:149], v[194:197], v[74:77]
	v_mfma_f32_16x16x32_bf16 v[126:129], v[142:145], v[174:177], v[126:129]
	v_mfma_f32_16x16x32_bf16 v[122:125], v[150:153], v[174:177], v[122:125]
	v_mfma_f32_16x16x32_bf16 v[110:113], v[142:145], v[182:185], v[110:113]
	v_mfma_f32_16x16x32_bf16 v[106:109], v[150:153], v[182:185], v[106:109]
	v_mfma_f32_16x16x32_bf16 v[94:97], v[142:145], v[190:193], v[94:97]
	v_mfma_f32_16x16x32_bf16 v[90:93], v[150:153], v[190:193], v[90:93]
	v_mfma_f32_16x16x32_bf16 v[78:81], v[142:145], v[198:201], v[78:81]
	v_mfma_f32_16x16x32_bf16 v[74:77], v[150:153], v[198:201], v[74:77]
	s_setprio 0
	s_setprio 1
	v_mfma_f32_16x16x32_bf16 v[118:121], v[154:157], v[170:173], v[118:121]
	v_mfma_f32_16x16x32_bf16 v[114:117], v[162:165], v[170:173], v[114:117]
	v_mfma_f32_16x16x32_bf16 v[102:105], v[154:157], v[178:181], v[102:105]
	v_mfma_f32_16x16x32_bf16 v[98:101], v[162:165], v[178:181], v[98:101]
	v_mfma_f32_16x16x32_bf16 v[86:89], v[154:157], v[186:189], v[86:89]
	v_mfma_f32_16x16x32_bf16 v[82:85], v[162:165], v[186:189], v[82:85]
	v_mfma_f32_16x16x32_bf16 v[70:73], v[154:157], v[194:197], v[70:73]
	v_mfma_f32_16x16x32_bf16 v[66:69], v[162:165], v[194:197], v[66:69]
	v_mfma_f32_16x16x32_bf16 v[118:121], v[158:161], v[174:177], v[118:121]
	v_mfma_f32_16x16x32_bf16 v[114:117], v[166:169], v[174:177], v[114:117]
	v_mfma_f32_16x16x32_bf16 v[102:105], v[158:161], v[182:185], v[102:105]
	v_mfma_f32_16x16x32_bf16 v[98:101], v[166:169], v[182:185], v[98:101]
	v_mfma_f32_16x16x32_bf16 v[86:89], v[158:161], v[190:193], v[86:89]
	v_mfma_f32_16x16x32_bf16 v[82:85], v[166:169], v[190:193], v[82:85]
	v_mfma_f32_16x16x32_bf16 v[70:73], v[158:161], v[198:201], v[70:73]
	v_mfma_f32_16x16x32_bf16 v[66:69], v[166:169], v[198:201], v[66:69]
	s_setprio 0
	s_barrier
	s_add_i32 s51, s51, s26
	ds_read_b128 v[170:173], v136 offset:16384
	ds_read_b128 v[174:177], v136 offset:17408
	ds_read_b128 v[178:181], v136 offset:18432
	ds_read_b128 v[182:185], v136 offset:19456
	ds_read_b128 v[186:189], v136 offset:20480
	ds_read_b128 v[190:193], v136 offset:21504
	ds_read_b128 v[194:197], v136 offset:22528
	ds_read_b128 v[198:201], v136 offset:23552
	s_mov_b32 m0, s51
	s_nop 0
	global_load_lds_dwordx4 v133, s[16:17]
	s_add_i32 m0, s51, 0x2000
	s_add_u32 s58, s16, 0xb0000
	global_load_lds_dwordx4 v134, s[16:17]
	s_addc_u32 s59, s17, 0
	s_add_i32 s51, s60, s26
	s_mov_b32 m0, s51
	s_nop 0
	global_load_lds_dwordx4 v133, s[58:59]
	s_add_i32 m0, s51, 0x2000
	s_nop 0
	global_load_lds_dwordx4 v134, s[58:59]
	s_mov_b32 m0, s37
	s_nop 0
	global_load_lds_dwordx4 v130, s[14:15]
	s_mov_b32 m0, s40
	s_nop 0
	global_load_lds_dwordx4 v131, s[14:15]
	s_waitcnt vmcnt(8)
	s_waitcnt lgkmcnt(0)
	s_setprio 1
	s_barrier
	v_mfma_f32_16x16x32_bf16 v[62:65], v[138:141], v[170:173], v[62:65]
	v_mfma_f32_16x16x32_bf16 v[58:61], v[146:149], v[170:173], v[58:61]
	v_mfma_f32_16x16x32_bf16 v[46:49], v[138:141], v[178:181], v[46:49]
	v_mfma_f32_16x16x32_bf16 v[42:45], v[146:149], v[178:181], v[42:45]
	v_mfma_f32_16x16x32_bf16 v[30:33], v[138:141], v[186:189], v[30:33]
	v_mfma_f32_16x16x32_bf16 v[26:29], v[146:149], v[186:189], v[26:29]
	v_mfma_f32_16x16x32_bf16 v[14:17], v[138:141], v[194:197], v[14:17]
	v_mfma_f32_16x16x32_bf16 v[10:13], v[146:149], v[194:197], v[10:13]
	v_mfma_f32_16x16x32_bf16 v[62:65], v[142:145], v[174:177], v[62:65]
	v_mfma_f32_16x16x32_bf16 v[58:61], v[150:153], v[174:177], v[58:61]
	v_mfma_f32_16x16x32_bf16 v[46:49], v[142:145], v[182:185], v[46:49]
	v_mfma_f32_16x16x32_bf16 v[42:45], v[150:153], v[182:185], v[42:45]
	v_mfma_f32_16x16x32_bf16 v[30:33], v[142:145], v[190:193], v[30:33]
	v_mfma_f32_16x16x32_bf16 v[26:29], v[150:153], v[190:193], v[26:29]
	v_mfma_f32_16x16x32_bf16 v[14:17], v[142:145], v[198:201], v[14:17]
	v_mfma_f32_16x16x32_bf16 v[10:13], v[150:153], v[198:201], v[10:13]
	s_setprio 0
	s_setprio 1
	v_mfma_f32_16x16x32_bf16 v[54:57], v[154:157], v[170:173], v[54:57]
	v_mfma_f32_16x16x32_bf16 v[50:53], v[162:165], v[170:173], v[50:53]
	v_mfma_f32_16x16x32_bf16 v[38:41], v[154:157], v[178:181], v[38:41]
	v_mfma_f32_16x16x32_bf16 v[34:37], v[162:165], v[178:181], v[34:37]
	v_mfma_f32_16x16x32_bf16 v[22:25], v[154:157], v[186:189], v[22:25]
	v_mfma_f32_16x16x32_bf16 v[18:21], v[162:165], v[186:189], v[18:21]
	v_mfma_f32_16x16x32_bf16 v[6:9], v[154:157], v[194:197], v[6:9]
	v_mfma_f32_16x16x32_bf16 v[2:5], v[162:165], v[194:197], v[2:5]
	v_mfma_f32_16x16x32_bf16 v[54:57], v[158:161], v[174:177], v[54:57]
	v_mfma_f32_16x16x32_bf16 v[50:53], v[166:169], v[174:177], v[50:53]
	v_mfma_f32_16x16x32_bf16 v[38:41], v[158:161], v[182:185], v[38:41]
	v_mfma_f32_16x16x32_bf16 v[34:37], v[166:169], v[182:185], v[34:37]
	v_mfma_f32_16x16x32_bf16 v[22:25], v[158:161], v[190:193], v[22:25]
	v_mfma_f32_16x16x32_bf16 v[18:21], v[166:169], v[190:193], v[18:21]
	v_mfma_f32_16x16x32_bf16 v[6:9], v[158:161], v[198:201], v[6:9]
	v_mfma_f32_16x16x32_bf16 v[2:5], v[166:169], v[198:201], v[2:5]
	s_setprio 0
	s_barrier
	s_add_i32 s51, 0, 0x18000
	s_add_i32 s60, 0, 0x1c000
	ds_read_b128 v[138:141], v0 offset:32768
	ds_read_b128 v[142:145], v0 offset:33792
	ds_read_b128 v[146:149], v0 offset:34816
	ds_read_b128 v[150:153], v0 offset:35840
	ds_read_b128 v[154:157], v0 offset:49152
	ds_read_b128 v[158:161], v0 offset:50176
	ds_read_b128 v[162:165], v0 offset:51200
	ds_read_b128 v[166:169], v0 offset:52224
	s_add_u32 s58, s14, 0xb0000
	s_mov_b32 m0, s41
	ds_read_b128 v[170:173], v136 offset:32768
	ds_read_b128 v[174:177], v136 offset:33792
	ds_read_b128 v[178:181], v136 offset:34816
	ds_read_b128 v[182:185], v136 offset:35840
	ds_read_b128 v[186:189], v136 offset:36864
	ds_read_b128 v[190:193], v136 offset:37888
	ds_read_b128 v[194:197], v136 offset:38912
	ds_read_b128 v[198:201], v136 offset:39936
	s_addc_u32 s59, s15, 0
	s_nop 0
	global_load_lds_dwordx4 v130, s[58:59]
	s_mov_b32 m0, s42
	s_nop 0
	global_load_lds_dwordx4 v131, s[58:59]
	s_waitcnt vmcnt(8)
	s_waitcnt lgkmcnt(0)
	s_setprio 1
	s_barrier
	v_mfma_f32_16x16x32_bf16 v[126:129], v[138:141], v[170:173], v[126:129]
	v_mfma_f32_16x16x32_bf16 v[122:125], v[146:149], v[170:173], v[122:125]
	v_mfma_f32_16x16x32_bf16 v[110:113], v[138:141], v[178:181], v[110:113]
	v_mfma_f32_16x16x32_bf16 v[106:109], v[146:149], v[178:181], v[106:109]
	v_mfma_f32_16x16x32_bf16 v[94:97], v[138:141], v[186:189], v[94:97]
	v_mfma_f32_16x16x32_bf16 v[90:93], v[146:149], v[186:189], v[90:93]
	v_mfma_f32_16x16x32_bf16 v[78:81], v[138:141], v[194:197], v[78:81]
	v_mfma_f32_16x16x32_bf16 v[74:77], v[146:149], v[194:197], v[74:77]
	v_mfma_f32_16x16x32_bf16 v[126:129], v[142:145], v[174:177], v[126:129]
	v_mfma_f32_16x16x32_bf16 v[122:125], v[150:153], v[174:177], v[122:125]
	v_mfma_f32_16x16x32_bf16 v[110:113], v[142:145], v[182:185], v[110:113]
	v_mfma_f32_16x16x32_bf16 v[106:109], v[150:153], v[182:185], v[106:109]
	v_mfma_f32_16x16x32_bf16 v[94:97], v[142:145], v[190:193], v[94:97]
	v_mfma_f32_16x16x32_bf16 v[90:93], v[150:153], v[190:193], v[90:93]
	v_mfma_f32_16x16x32_bf16 v[78:81], v[142:145], v[198:201], v[78:81]
	v_mfma_f32_16x16x32_bf16 v[74:77], v[150:153], v[198:201], v[74:77]
	s_setprio 0
	s_setprio 1
	v_mfma_f32_16x16x32_bf16 v[118:121], v[154:157], v[170:173], v[118:121]
	v_mfma_f32_16x16x32_bf16 v[114:117], v[162:165], v[170:173], v[114:117]
	v_mfma_f32_16x16x32_bf16 v[102:105], v[154:157], v[178:181], v[102:105]
	v_mfma_f32_16x16x32_bf16 v[98:101], v[162:165], v[178:181], v[98:101]
	v_mfma_f32_16x16x32_bf16 v[86:89], v[154:157], v[186:189], v[86:89]
	v_mfma_f32_16x16x32_bf16 v[82:85], v[162:165], v[186:189], v[82:85]
	v_mfma_f32_16x16x32_bf16 v[70:73], v[154:157], v[194:197], v[70:73]
	v_mfma_f32_16x16x32_bf16 v[66:69], v[162:165], v[194:197], v[66:69]
	v_mfma_f32_16x16x32_bf16 v[118:121], v[158:161], v[174:177], v[118:121]
	v_mfma_f32_16x16x32_bf16 v[114:117], v[166:169], v[174:177], v[114:117]
	v_mfma_f32_16x16x32_bf16 v[102:105], v[158:161], v[182:185], v[102:105]
	v_mfma_f32_16x16x32_bf16 v[98:101], v[166:169], v[182:185], v[98:101]
	v_mfma_f32_16x16x32_bf16 v[86:89], v[158:161], v[190:193], v[86:89]
	v_mfma_f32_16x16x32_bf16 v[82:85], v[166:169], v[190:193], v[82:85]
	v_mfma_f32_16x16x32_bf16 v[70:73], v[158:161], v[198:201], v[70:73]
	v_mfma_f32_16x16x32_bf16 v[66:69], v[166:169], v[198:201], v[66:69]
	s_setprio 0
	s_barrier
	ds_read_b128 v[170:173], v136 offset:49152
	ds_read_b128 v[174:177], v136 offset:50176
	ds_read_b128 v[178:181], v136 offset:51200
	ds_read_b128 v[182:185], v136 offset:52224
	ds_read_b128 v[186:189], v136 offset:53248
	ds_read_b128 v[190:193], v136 offset:54272
	ds_read_b128 v[194:197], v136 offset:55296
	ds_read_b128 v[198:201], v136 offset:56320
	s_add_i32 s51, s51, s26
	s_add_u32 s100, s16, s38
	s_addc_u32 s101, s17, s39
	s_mov_b32 m0, s51
	s_nop 0
	global_load_lds_dwordx4 v133, s[100:101]
	s_add_i32 m0, s51, 0x2000
	s_nop 0
	s_add_u32 s16, s16, 0xb0080
	s_addc_u32 s17, s17, 0
	s_add_i32 s51, s60, s26
	global_load_lds_dwordx4 v134, s[100:101]
	s_mov_b32 m0, s51
	s_nop 0
	global_load_lds_dwordx4 v133, s[16:17]
	s_add_i32 m0, s51, 0x2000
	s_nop 0
	global_load_lds_dwordx4 v134, s[16:17]
	s_mov_b32 m0, s48
	s_add_u32 s100, s14, s38
	s_addc_u32 s101, s15, s39
	v_mov_b32_e32 v0, v131
	global_load_lds_dwordx4 v130, s[100:101]
	s_mov_b32 m0, s49
	s_nop 0
	global_load_lds_dwordx4 v131, s[100:101]
	s_waitcnt vmcnt(8)
	s_waitcnt lgkmcnt(0)
	s_setprio 1
	s_barrier
	v_mfma_f32_16x16x32_bf16 v[62:65], v[138:141], v[170:173], v[62:65]
	v_mfma_f32_16x16x32_bf16 v[58:61], v[146:149], v[170:173], v[58:61]
	v_mfma_f32_16x16x32_bf16 v[46:49], v[138:141], v[178:181], v[46:49]
	v_mfma_f32_16x16x32_bf16 v[42:45], v[146:149], v[178:181], v[42:45]
	v_mfma_f32_16x16x32_bf16 v[30:33], v[138:141], v[186:189], v[30:33]
	v_mfma_f32_16x16x32_bf16 v[26:29], v[146:149], v[186:189], v[26:29]
	v_mfma_f32_16x16x32_bf16 v[14:17], v[138:141], v[194:197], v[14:17]
	v_mfma_f32_16x16x32_bf16 v[10:13], v[146:149], v[194:197], v[10:13]
	v_mfma_f32_16x16x32_bf16 v[62:65], v[142:145], v[174:177], v[62:65]
	v_mfma_f32_16x16x32_bf16 v[58:61], v[150:153], v[174:177], v[58:61]
	v_mfma_f32_16x16x32_bf16 v[46:49], v[142:145], v[182:185], v[46:49]
	v_mfma_f32_16x16x32_bf16 v[42:45], v[150:153], v[182:185], v[42:45]
	v_mfma_f32_16x16x32_bf16 v[30:33], v[142:145], v[190:193], v[30:33]
	v_mfma_f32_16x16x32_bf16 v[26:29], v[150:153], v[190:193], v[26:29]
	v_mfma_f32_16x16x32_bf16 v[14:17], v[142:145], v[198:201], v[14:17]
	v_mfma_f32_16x16x32_bf16 v[10:13], v[150:153], v[198:201], v[10:13]
	s_setprio 0
	s_setprio 1
	v_mfma_f32_16x16x32_bf16 v[54:57], v[154:157], v[170:173], v[54:57]
	v_mfma_f32_16x16x32_bf16 v[50:53], v[162:165], v[170:173], v[50:53]
	v_mfma_f32_16x16x32_bf16 v[38:41], v[154:157], v[178:181], v[38:41]
	v_mfma_f32_16x16x32_bf16 v[34:37], v[162:165], v[178:181], v[34:37]
	v_mfma_f32_16x16x32_bf16 v[22:25], v[154:157], v[186:189], v[22:25]
	v_mfma_f32_16x16x32_bf16 v[18:21], v[162:165], v[186:189], v[18:21]
	v_mfma_f32_16x16x32_bf16 v[6:9], v[154:157], v[194:197], v[6:9]
	v_mfma_f32_16x16x32_bf16 v[2:5], v[162:165], v[194:197], v[2:5]
	v_mfma_f32_16x16x32_bf16 v[54:57], v[158:161], v[174:177], v[54:57]
	v_mfma_f32_16x16x32_bf16 v[50:53], v[166:169], v[174:177], v[50:53]
	v_mfma_f32_16x16x32_bf16 v[38:41], v[158:161], v[182:185], v[38:41]
	v_mfma_f32_16x16x32_bf16 v[34:37], v[166:169], v[182:185], v[34:37]
	v_mfma_f32_16x16x32_bf16 v[22:25], v[158:161], v[190:193], v[22:25]
	v_mfma_f32_16x16x32_bf16 v[18:21], v[166:169], v[190:193], v[18:21]
	v_mfma_f32_16x16x32_bf16 v[6:9], v[158:161], v[198:201], v[6:9]
	v_mfma_f32_16x16x32_bf16 v[2:5], v[166:169], v[198:201], v[2:5]
	s_setprio 0
	s_barrier
	s_add_i32 s50, s50, 2
	s_add_u32 s2, s2, 0x100
	s_addc_u32 s3, s3, 0
	s_cmp_gt_u32 s50, 41
	s_cbranch_scc0 .LBB0_953

.LBB0_1087:
	s_add_u32 s2, s6, 0x40080
	s_addc_u32 s3, s7, 0
	s_add_u32 s8, s8, 0x100
	s_addc_u32 s9, s9, 0
	s_mov_b32 s22, -2
	s_add_u32 s4, s2, 0xfffc0080
	s_addc_u32 s5, s3, -1
	s_add_i32 s23, 0, 0x10000
	s_cmp_eq_u32 s22, 12
	s_cselect_b32 s5, s49, s5
	s_cselect_b32 s4, s48, s4
	s_waitcnt vmcnt(0)
	v_add_u32_e32 v0, s23, v145
	s_cselect_b32 s7, s97, s9
	s_cselect_b32 s6, s96, s8
	s_add_i32 s25, 0, 0x14000
	ds_read_b128 v[146:149], v0
	ds_read_b128 v[152:155], v0 offset:1024
	ds_read_b128 v[156:159], v0 offset:2048
	ds_read_b128 v[160:163], v0 offset:3072
	ds_read_b128 v[164:167], v0 offset:16384
	ds_read_b128 v[168:171], v0 offset:17408
	ds_read_b128 v[172:175], v0 offset:18432
	ds_read_b128 v[176:179], v0 offset:19456
	ds_read_b128 v[180:183], v150
	ds_read_b128 v[184:187], v150 offset:1024
	ds_read_b128 v[188:191], v150 offset:2048
	ds_read_b128 v[192:195], v150 offset:3072
	ds_read_b128 v[196:199], v150 offset:4096
	ds_read_b128 v[200:203], v150 offset:5120
	ds_read_b128 v[204:207], v150 offset:6144
	ds_read_b128 v[208:211], v150 offset:7168
	s_add_i32 m0, s60, 0xc000
	s_nop 0
	global_load_lds_dwordx4 v131, s[2:3]
	s_add_i32 m0, s60, 0xe000
	s_nop 0
	global_load_lds_dwordx4 v133, s[2:3]
	s_waitcnt vmcnt(8)
	s_waitcnt lgkmcnt(0)
	s_setprio 1
	s_barrier
	v_mfma_f32_16x16x32_bf16 v[126:129], v[146:149], v[180:183], 0
	v_mfma_f32_16x16x32_bf16 v[122:125], v[156:159], v[180:183], 0
	v_mfma_f32_16x16x32_bf16 v[110:113], v[146:149], v[188:191], 0
	v_mfma_f32_16x16x32_bf16 v[106:109], v[156:159], v[188:191], 0
	v_mfma_f32_16x16x32_bf16 v[94:97], v[146:149], v[196:199], 0
	v_mfma_f32_16x16x32_bf16 v[90:93], v[156:159], v[196:199], 0
	v_mfma_f32_16x16x32_bf16 v[78:81], v[146:149], v[204:207], 0
	v_mfma_f32_16x16x32_bf16 v[74:77], v[156:159], v[204:207], 0
	v_mfma_f32_16x16x32_bf16 v[126:129], v[152:155], v[184:187], v[126:129]
	v_mfma_f32_16x16x32_bf16 v[122:125], v[160:163], v[184:187], v[122:125]
	v_mfma_f32_16x16x32_bf16 v[110:113], v[152:155], v[192:195], v[110:113]
	v_mfma_f32_16x16x32_bf16 v[106:109], v[160:163], v[192:195], v[106:109]
	v_mfma_f32_16x16x32_bf16 v[94:97], v[152:155], v[200:203], v[94:97]
	v_mfma_f32_16x16x32_bf16 v[90:93], v[160:163], v[200:203], v[90:93]
	v_mfma_f32_16x16x32_bf16 v[78:81], v[152:155], v[208:211], v[78:81]
	v_mfma_f32_16x16x32_bf16 v[74:77], v[160:163], v[208:211], v[74:77]
	s_setprio 0
	s_setprio 1
	v_mfma_f32_16x16x32_bf16 v[118:121], v[164:167], v[180:183], 0
	v_mfma_f32_16x16x32_bf16 v[114:117], v[172:175], v[180:183], 0
	v_mfma_f32_16x16x32_bf16 v[102:105], v[164:167], v[188:191], 0
	v_mfma_f32_16x16x32_bf16 v[98:101], v[172:175], v[188:191], 0
	v_mfma_f32_16x16x32_bf16 v[86:89], v[164:167], v[196:199], 0
	v_mfma_f32_16x16x32_bf16 v[82:85], v[172:175], v[196:199], 0
	v_mfma_f32_16x16x32_bf16 v[70:73], v[164:167], v[204:207], 0
	v_mfma_f32_16x16x32_bf16 v[66:69], v[172:175], v[204:207], 0
	v_mfma_f32_16x16x32_bf16 v[118:121], v[168:171], v[184:187], v[118:121]
	v_mfma_f32_16x16x32_bf16 v[114:117], v[176:179], v[184:187], v[114:117]
	v_mfma_f32_16x16x32_bf16 v[102:105], v[168:171], v[192:195], v[102:105]
	v_mfma_f32_16x16x32_bf16 v[98:101], v[176:179], v[192:195], v[98:101]
	v_mfma_f32_16x16x32_bf16 v[86:89], v[168:171], v[200:203], v[86:89]
	v_mfma_f32_16x16x32_bf16 v[82:85], v[176:179], v[200:203], v[82:85]
	v_mfma_f32_16x16x32_bf16 v[70:73], v[168:171], v[208:211], v[70:73]
	v_mfma_f32_16x16x32_bf16 v[66:69], v[176:179], v[208:211], v[66:69]
	s_setprio 0
	s_barrier
	s_add_i32 s23, s23, s42
	ds_read_b128 v[180:183], v150 offset:16384
	ds_read_b128 v[184:187], v150 offset:17408
	ds_read_b128 v[188:191], v150 offset:18432
	ds_read_b128 v[192:195], v150 offset:19456
	ds_read_b128 v[196:199], v150 offset:20480
	ds_read_b128 v[200:203], v150 offset:21504
	ds_read_b128 v[204:207], v150 offset:22528
	ds_read_b128 v[208:211], v150 offset:23552
	s_mov_b32 m0, s23
	s_nop 0
	global_load_lds_dwordx4 v137, s[6:7]
	s_add_i32 m0, s23, 0x2000
	s_add_u32 s46, s6, 0x40000
	global_load_lds_dwordx4 v139, s[6:7]
	s_addc_u32 s47, s7, 0
	s_add_i32 s23, s25, s42
	s_mov_b32 m0, s23
	s_nop 0
	global_load_lds_dwordx4 v137, s[46:47]
	s_add_i32 m0, s23, 0x2000
	s_nop 0
	global_load_lds_dwordx4 v139, s[46:47]
	s_mov_b32 m0, s60
	s_nop 0
	global_load_lds_dwordx4 v131, s[4:5]
	s_mov_b32 m0, s61
	s_nop 0
	global_load_lds_dwordx4 v133, s[4:5]
	s_waitcnt vmcnt(8)
	s_waitcnt lgkmcnt(0)
	s_setprio 1
	s_barrier
	v_mfma_f32_16x16x32_bf16 v[62:65], v[146:149], v[180:183], 0
	v_mfma_f32_16x16x32_bf16 v[58:61], v[156:159], v[180:183], 0
	v_mfma_f32_16x16x32_bf16 v[46:49], v[146:149], v[188:191], 0
	v_mfma_f32_16x16x32_bf16 v[42:45], v[156:159], v[188:191], 0
	v_mfma_f32_16x16x32_bf16 v[30:33], v[146:149], v[196:199], 0
	v_mfma_f32_16x16x32_bf16 v[26:29], v[156:159], v[196:199], 0
	v_mfma_f32_16x16x32_bf16 v[14:17], v[146:149], v[204:207], 0
	v_mfma_f32_16x16x32_bf16 v[10:13], v[156:159], v[204:207], 0
	v_mfma_f32_16x16x32_bf16 v[62:65], v[152:155], v[184:187], v[62:65]
	v_mfma_f32_16x16x32_bf16 v[58:61], v[160:163], v[184:187], v[58:61]
	v_mfma_f32_16x16x32_bf16 v[46:49], v[152:155], v[192:195], v[46:49]
	v_mfma_f32_16x16x32_bf16 v[42:45], v[160:163], v[192:195], v[42:45]
	v_mfma_f32_16x16x32_bf16 v[30:33], v[152:155], v[200:203], v[30:33]
	v_mfma_f32_16x16x32_bf16 v[26:29], v[160:163], v[200:203], v[26:29]
	v_mfma_f32_16x16x32_bf16 v[14:17], v[152:155], v[208:211], v[14:17]
	v_mfma_f32_16x16x32_bf16 v[10:13], v[160:163], v[208:211], v[10:13]
	s_setprio 0
	s_setprio 1
	v_mfma_f32_16x16x32_bf16 v[54:57], v[164:167], v[180:183], 0
	v_mfma_f32_16x16x32_bf16 v[50:53], v[172:175], v[180:183], 0
	v_mfma_f32_16x16x32_bf16 v[38:41], v[164:167], v[188:191], 0
	v_mfma_f32_16x16x32_bf16 v[34:37], v[172:175], v[188:191], 0
	v_mfma_f32_16x16x32_bf16 v[22:25], v[164:167], v[196:199], 0
	v_mfma_f32_16x16x32_bf16 v[18:21], v[172:175], v[196:199], 0
	v_mfma_f32_16x16x32_bf16 v[6:9], v[164:167], v[204:207], 0
	v_mfma_f32_16x16x32_bf16 v[2:5], v[172:175], v[204:207], 0
	v_mfma_f32_16x16x32_bf16 v[54:57], v[168:171], v[184:187], v[54:57]
	v_mfma_f32_16x16x32_bf16 v[50:53], v[176:179], v[184:187], v[50:53]
	v_mfma_f32_16x16x32_bf16 v[38:41], v[168:171], v[192:195], v[38:41]
	v_mfma_f32_16x16x32_bf16 v[34:37], v[176:179], v[192:195], v[34:37]
	v_mfma_f32_16x16x32_bf16 v[22:25], v[168:171], v[200:203], v[22:25]
	v_mfma_f32_16x16x32_bf16 v[18:21], v[176:179], v[200:203], v[18:21]
	v_mfma_f32_16x16x32_bf16 v[6:9], v[168:171], v[208:211], v[6:9]
	v_mfma_f32_16x16x32_bf16 v[2:5], v[176:179], v[208:211], v[2:5]
	s_setprio 0
	s_barrier
	s_add_i32 s23, 0, 0x18000
	s_add_i32 s25, 0, 0x1c000
	ds_read_b128 v[146:149], v0 offset:32768
	ds_read_b128 v[152:155], v0 offset:33792
	ds_read_b128 v[156:159], v0 offset:34816
	ds_read_b128 v[160:163], v0 offset:35840
	ds_read_b128 v[164:167], v0 offset:49152
	ds_read_b128 v[168:171], v0 offset:50176
	ds_read_b128 v[172:175], v0 offset:51200
	ds_read_b128 v[176:179], v0 offset:52224
	s_add_u32 s46, s4, 0x40000
	s_mov_b32 m0, s66
	ds_read_b128 v[180:183], v150 offset:32768
	ds_read_b128 v[184:187], v150 offset:33792
	ds_read_b128 v[188:191], v150 offset:34816
	ds_read_b128 v[192:195], v150 offset:35840
	ds_read_b128 v[196:199], v150 offset:36864
	ds_read_b128 v[200:203], v150 offset:37888
	ds_read_b128 v[204:207], v150 offset:38912
	ds_read_b128 v[208:211], v150 offset:39936
	s_addc_u32 s47, s5, 0
	s_nop 0
	global_load_lds_dwordx4 v131, s[46:47]
	s_mov_b32 m0, s67
	s_nop 0
	global_load_lds_dwordx4 v133, s[46:47]
	s_waitcnt vmcnt(8)
	s_waitcnt lgkmcnt(0)
	s_setprio 1
	s_barrier
	v_mfma_f32_16x16x32_bf16 v[126:129], v[146:149], v[180:183], v[126:129]
	v_mfma_f32_16x16x32_bf16 v[122:125], v[156:159], v[180:183], v[122:125]
	v_mfma_f32_16x16x32_bf16 v[110:113], v[146:149], v[188:191], v[110:113]
	v_mfma_f32_16x16x32_bf16 v[106:109], v[156:159], v[188:191], v[106:109]
	v_mfma_f32_16x16x32_bf16 v[94:97], v[146:149], v[196:199], v[94:97]
	v_mfma_f32_16x16x32_bf16 v[90:93], v[156:159], v[196:199], v[90:93]
	v_mfma_f32_16x16x32_bf16 v[78:81], v[146:149], v[204:207], v[78:81]
	v_mfma_f32_16x16x32_bf16 v[74:77], v[156:159], v[204:207], v[74:77]
	v_mfma_f32_16x16x32_bf16 v[126:129], v[152:155], v[184:187], v[126:129]
	v_mfma_f32_16x16x32_bf16 v[122:125], v[160:163], v[184:187], v[122:125]
	v_mfma_f32_16x16x32_bf16 v[110:113], v[152:155], v[192:195], v[110:113]
	v_mfma_f32_16x16x32_bf16 v[106:109], v[160:163], v[192:195], v[106:109]
	v_mfma_f32_16x16x32_bf16 v[94:97], v[152:155], v[200:203], v[94:97]
	v_mfma_f32_16x16x32_bf16 v[90:93], v[160:163], v[200:203], v[90:93]
	v_mfma_f32_16x16x32_bf16 v[78:81], v[152:155], v[208:211], v[78:81]
	v_mfma_f32_16x16x32_bf16 v[74:77], v[160:163], v[208:211], v[74:77]
	s_setprio 0
	s_setprio 1
	v_mfma_f32_16x16x32_bf16 v[118:121], v[164:167], v[180:183], v[118:121]
	v_mfma_f32_16x16x32_bf16 v[114:117], v[172:175], v[180:183], v[114:117]
	v_mfma_f32_16x16x32_bf16 v[102:105], v[164:167], v[188:191], v[102:105]
	v_mfma_f32_16x16x32_bf16 v[98:101], v[172:175], v[188:191], v[98:101]
	v_mfma_f32_16x16x32_bf16 v[86:89], v[164:167], v[196:199], v[86:89]
	v_mfma_f32_16x16x32_bf16 v[82:85], v[172:175], v[196:199], v[82:85]
	v_mfma_f32_16x16x32_bf16 v[70:73], v[164:167], v[204:207], v[70:73]
	v_mfma_f32_16x16x32_bf16 v[66:69], v[172:175], v[204:207], v[66:69]
	v_mfma_f32_16x16x32_bf16 v[118:121], v[168:171], v[184:187], v[118:121]
	v_mfma_f32_16x16x32_bf16 v[114:117], v[176:179], v[184:187], v[114:117]
	v_mfma_f32_16x16x32_bf16 v[102:105], v[168:171], v[192:195], v[102:105]
	v_mfma_f32_16x16x32_bf16 v[98:101], v[176:179], v[192:195], v[98:101]
	v_mfma_f32_16x16x32_bf16 v[86:89], v[168:171], v[200:203], v[86:89]
	v_mfma_f32_16x16x32_bf16 v[82:85], v[176:179], v[200:203], v[82:85]
	v_mfma_f32_16x16x32_bf16 v[70:73], v[168:171], v[208:211], v[70:73]
	v_mfma_f32_16x16x32_bf16 v[66:69], v[176:179], v[208:211], v[66:69]
	s_setprio 0
	s_barrier
	ds_read_b128 v[180:183], v150 offset:49152
	ds_read_b128 v[184:187], v150 offset:50176
	ds_read_b128 v[188:191], v150 offset:51200
	ds_read_b128 v[192:195], v150 offset:52224
	ds_read_b128 v[196:199], v150 offset:53248
	ds_read_b128 v[200:203], v150 offset:54272
	ds_read_b128 v[204:207], v150 offset:55296
	ds_read_b128 v[208:211], v150 offset:56320
	s_add_i32 s23, s23, s42
	s_add_u32 s100, s6, s38
	s_addc_u32 s101, s7, s39
	s_mov_b32 m0, s23
	s_nop 0
	global_load_lds_dwordx4 v137, s[100:101]
	s_add_i32 m0, s23, 0x2000
	s_nop 0
	s_add_u32 s6, s6, 0x40080
	s_addc_u32 s7, s7, 0
	s_add_i32 s23, s25, s42
	global_load_lds_dwordx4 v139, s[100:101]
	s_mov_b32 m0, s23
	s_nop 0
	global_load_lds_dwordx4 v137, s[6:7]
	s_add_i32 m0, s23, 0x2000
	s_nop 0
	global_load_lds_dwordx4 v139, s[6:7]
	s_mov_b32 m0, s70
	s_add_u32 s100, s4, s38
	s_addc_u32 s101, s5, s39
	v_mov_b32_e32 v0, v133
	global_load_lds_dwordx4 v131, s[100:101]
	s_mov_b32 m0, s71
	s_nop 0
	global_load_lds_dwordx4 v133, s[100:101]
	s_waitcnt vmcnt(8)
	s_waitcnt lgkmcnt(0)
	s_setprio 1
	s_barrier
	v_mfma_f32_16x16x32_bf16 v[62:65], v[146:149], v[180:183], v[62:65]
	v_mfma_f32_16x16x32_bf16 v[58:61], v[156:159], v[180:183], v[58:61]
	v_mfma_f32_16x16x32_bf16 v[46:49], v[146:149], v[188:191], v[46:49]
	v_mfma_f32_16x16x32_bf16 v[42:45], v[156:159], v[188:191], v[42:45]
	v_mfma_f32_16x16x32_bf16 v[30:33], v[146:149], v[196:199], v[30:33]
	v_mfma_f32_16x16x32_bf16 v[26:29], v[156:159], v[196:199], v[26:29]
	v_mfma_f32_16x16x32_bf16 v[14:17], v[146:149], v[204:207], v[14:17]
	v_mfma_f32_16x16x32_bf16 v[10:13], v[156:159], v[204:207], v[10:13]
	v_mfma_f32_16x16x32_bf16 v[62:65], v[152:155], v[184:187], v[62:65]
	v_mfma_f32_16x16x32_bf16 v[58:61], v[160:163], v[184:187], v[58:61]
	v_mfma_f32_16x16x32_bf16 v[46:49], v[152:155], v[192:195], v[46:49]
	v_mfma_f32_16x16x32_bf16 v[42:45], v[160:163], v[192:195], v[42:45]
	v_mfma_f32_16x16x32_bf16 v[30:33], v[152:155], v[200:203], v[30:33]
	v_mfma_f32_16x16x32_bf16 v[26:29], v[160:163], v[200:203], v[26:29]
	v_mfma_f32_16x16x32_bf16 v[14:17], v[152:155], v[208:211], v[14:17]
	v_mfma_f32_16x16x32_bf16 v[10:13], v[160:163], v[208:211], v[10:13]
	s_setprio 0
	s_setprio 1
	v_mfma_f32_16x16x32_bf16 v[54:57], v[164:167], v[180:183], v[54:57]
	v_mfma_f32_16x16x32_bf16 v[50:53], v[172:175], v[180:183], v[50:53]
	v_mfma_f32_16x16x32_bf16 v[38:41], v[164:167], v[188:191], v[38:41]
	v_mfma_f32_16x16x32_bf16 v[34:37], v[172:175], v[188:191], v[34:37]
	v_mfma_f32_16x16x32_bf16 v[22:25], v[164:167], v[196:199], v[22:25]
	v_mfma_f32_16x16x32_bf16 v[18:21], v[172:175], v[196:199], v[18:21]
	v_mfma_f32_16x16x32_bf16 v[6:9], v[164:167], v[204:207], v[6:9]
	v_mfma_f32_16x16x32_bf16 v[2:5], v[172:175], v[204:207], v[2:5]
	v_mfma_f32_16x16x32_bf16 v[54:57], v[168:171], v[184:187], v[54:57]
	v_mfma_f32_16x16x32_bf16 v[50:53], v[176:179], v[184:187], v[50:53]
	v_mfma_f32_16x16x32_bf16 v[38:41], v[168:171], v[192:195], v[38:41]
	v_mfma_f32_16x16x32_bf16 v[34:37], v[176:179], v[192:195], v[34:37]
	v_mfma_f32_16x16x32_bf16 v[22:25], v[168:171], v[200:203], v[22:25]
	v_mfma_f32_16x16x32_bf16 v[18:21], v[176:179], v[200:203], v[18:21]
	v_mfma_f32_16x16x32_bf16 v[6:9], v[168:171], v[208:211], v[6:9]
	v_mfma_f32_16x16x32_bf16 v[2:5], v[176:179], v[208:211], v[2:5]
	s_setprio 0
	s_barrier
	s_add_i32 s22, s22, 2
	s_add_u32 s2, s2, 0x100
	s_addc_u32 s3, s3, 0
	s_add_u32 s8, s8, 0x100
	s_addc_u32 s9, s9, 0
	s_cmp_gt_u32 s22, 13
	s_cbranch_scc0 .LBB0_1088
	s_branch .Lpeel_exit_1088
	.p2align	6

.LBB0_1223:
	s_or_b64 exec, exec, s[10:11]
	s_waitcnt lgkmcnt(0)
	s_mov_b32 s6, s100
	s_nop 0
	v_add_u32_e32 v0, s6, v0
	v_and_b32_e32 v2, 31, v0
	v_cmp_ne_u32_e32 vcc, 31, v2
	s_and_saveexec_b64 s[6:7], vcc
	s_cbranch_execz .LBB0_1237
	s_load_dword s100, s[4:5], 0x0 glc
	s_movk_i32 s10, 0xffe0
	v_bitop3_b32 v0, v0, s10, v0 bitop3:0xc
	s_waitcnt lgkmcnt(0)
	v_add_u32_e32 v2, s100, v0
	v_cmp_gt_i32_e32 vcc, 0, v2
	s_and_b64 exec, exec, vcc
	s_cbranch_execz .LBB0_1237
	s_add_u32 s8, s8, 0x4200
	s_addc_u32 s9, s9, 0
	s_mov_b32 s24, 1
	s_mov_b64 s[10:11], 0
	s_branch .LBB0_1227

.LBB0_1681:
	s_add_u32 s48, s6, s2
	s_addc_u32 s49, s7, s3
	s_add_u32 s10, s48, 0x100
	s_addc_u32 s11, s49, 0
	s_add_u32 s12, s37, s2
	s_addc_u32 s13, s40, s3
	s_add_i32 s47, 0, 0x10000
	s_cmp_eq_u32 s46, 12
	s_cselect_b32 s11, s7, s11
	s_cselect_b32 s10, s6, s10
	v_add_u32_e32 v0, s47, v136
	s_cselect_b32 s13, s9, s13
	s_cselect_b32 s12, s8, s12
	s_add_i32 s50, 0, 0x14000
	ds_read_b128 v[138:141], v0
	ds_read_b128 v[142:145], v0 offset:1024
	ds_read_b128 v[146:149], v0 offset:2048
	ds_read_b128 v[150:153], v0 offset:3072
	ds_read_b128 v[154:157], v0 offset:16384
	ds_read_b128 v[158:161], v0 offset:17408
	ds_read_b128 v[162:165], v0 offset:18432
	ds_read_b128 v[166:169], v0 offset:19456
	ds_read_b128 v[170:173], v137
	ds_read_b128 v[174:177], v137 offset:1024
	ds_read_b128 v[178:181], v137 offset:2048
	ds_read_b128 v[182:185], v137 offset:3072
	ds_read_b128 v[186:189], v137 offset:4096
	ds_read_b128 v[190:193], v137 offset:5120
	ds_read_b128 v[194:197], v137 offset:6144
	ds_read_b128 v[198:201], v137 offset:7168
	s_add_i32 m0, s23, 0xc000
	s_add_u32 s100, s48, s56
	s_addc_u32 s101, s49, s57
	global_load_lds_dwordx4 v130, s[100:101]
	s_add_i32 m0, s23, 0xe000
	s_nop 0
	global_load_lds_dwordx4 v132, s[100:101]
	s_waitcnt vmcnt(8)
	s_waitcnt lgkmcnt(0)
	s_setprio 1
	s_barrier
	v_mfma_f32_16x16x32_bf16 v[126:129], v[138:141], v[170:173], v[126:129]
	v_mfma_f32_16x16x32_bf16 v[122:125], v[146:149], v[170:173], v[122:125]
	v_mfma_f32_16x16x32_bf16 v[110:113], v[138:141], v[178:181], v[110:113]
	v_mfma_f32_16x16x32_bf16 v[106:109], v[146:149], v[178:181], v[106:109]
	v_mfma_f32_16x16x32_bf16 v[94:97], v[138:141], v[186:189], v[94:97]
	v_mfma_f32_16x16x32_bf16 v[90:93], v[146:149], v[186:189], v[90:93]
	v_mfma_f32_16x16x32_bf16 v[78:81], v[138:141], v[194:197], v[78:81]
	v_mfma_f32_16x16x32_bf16 v[74:77], v[146:149], v[194:197], v[74:77]
	v_mfma_f32_16x16x32_bf16 v[126:129], v[142:145], v[174:177], v[126:129]
	v_mfma_f32_16x16x32_bf16 v[122:125], v[150:153], v[174:177], v[122:125]
	v_mfma_f32_16x16x32_bf16 v[110:113], v[142:145], v[182:185], v[110:113]
	v_mfma_f32_16x16x32_bf16 v[106:109], v[150:153], v[182:185], v[106:109]
	v_mfma_f32_16x16x32_bf16 v[94:97], v[142:145], v[190:193], v[94:97]
	v_mfma_f32_16x16x32_bf16 v[90:93], v[150:153], v[190:193], v[90:93]
	v_mfma_f32_16x16x32_bf16 v[78:81], v[142:145], v[198:201], v[78:81]
	v_mfma_f32_16x16x32_bf16 v[74:77], v[150:153], v[198:201], v[74:77]
	s_setprio 0
	s_setprio 1
	v_mfma_f32_16x16x32_bf16 v[118:121], v[154:157], v[170:173], v[118:121]
	v_mfma_f32_16x16x32_bf16 v[114:117], v[162:165], v[170:173], v[114:117]
	v_mfma_f32_16x16x32_bf16 v[102:105], v[154:157], v[178:181], v[102:105]
	v_mfma_f32_16x16x32_bf16 v[98:101], v[162:165], v[178:181], v[98:101]
	v_mfma_f32_16x16x32_bf16 v[86:89], v[154:157], v[186:189], v[86:89]
	v_mfma_f32_16x16x32_bf16 v[82:85], v[162:165], v[186:189], v[82:85]
	v_mfma_f32_16x16x32_bf16 v[70:73], v[154:157], v[194:197], v[70:73]
	v_mfma_f32_16x16x32_bf16 v[66:69], v[162:165], v[194:197], v[66:69]
	v_mfma_f32_16x16x32_bf16 v[118:121], v[158:161], v[174:177], v[118:121]
	v_mfma_f32_16x16x32_bf16 v[114:117], v[166:169], v[174:177], v[114:117]
	v_mfma_f32_16x16x32_bf16 v[102:105], v[158:161], v[182:185], v[102:105]
	v_mfma_f32_16x16x32_bf16 v[98:101], v[166:169], v[182:185], v[98:101]
	v_mfma_f32_16x16x32_bf16 v[86:89], v[158:161], v[190:193], v[86:89]
	v_mfma_f32_16x16x32_bf16 v[82:85], v[166:169], v[190:193], v[82:85]
	v_mfma_f32_16x16x32_bf16 v[70:73], v[158:161], v[198:201], v[70:73]
	v_mfma_f32_16x16x32_bf16 v[66:69], v[166:169], v[198:201], v[66:69]
	s_setprio 0
	s_barrier
	s_add_i32 s47, s47, s22
	ds_read_b128 v[170:173], v137 offset:16384
	ds_read_b128 v[174:177], v137 offset:17408
	ds_read_b128 v[178:181], v137 offset:18432
	ds_read_b128 v[182:185], v137 offset:19456
	ds_read_b128 v[186:189], v137 offset:20480
	ds_read_b128 v[190:193], v137 offset:21504
	ds_read_b128 v[194:197], v137 offset:22528
	ds_read_b128 v[198:201], v137 offset:23552
	s_mov_b32 m0, s47
	s_nop 0
	global_load_lds_dwordx4 v134, s[12:13]
	s_add_i32 m0, s47, 0x2000
	s_add_u32 s48, s12, 0x40000
	global_load_lds_dwordx4 v135, s[12:13]
	s_addc_u32 s49, s13, 0
	s_add_i32 s47, s50, s22
	s_mov_b32 m0, s47
	s_nop 0
	global_load_lds_dwordx4 v134, s[48:49]
	s_add_i32 m0, s47, 0x2000
	s_nop 0
	global_load_lds_dwordx4 v135, s[48:49]
	s_mov_b32 m0, s23
	s_nop 0
	global_load_lds_dwordx4 v130, s[10:11]
	s_mov_b32 m0, s24
	s_nop 0
	global_load_lds_dwordx4 v132, s[10:11]
	s_waitcnt vmcnt(8)
	s_waitcnt lgkmcnt(0)
	s_setprio 1
	s_barrier
	v_mfma_f32_16x16x32_bf16 v[62:65], v[138:141], v[170:173], v[62:65]
	v_mfma_f32_16x16x32_bf16 v[58:61], v[146:149], v[170:173], v[58:61]
	v_mfma_f32_16x16x32_bf16 v[46:49], v[138:141], v[178:181], v[46:49]
	v_mfma_f32_16x16x32_bf16 v[42:45], v[146:149], v[178:181], v[42:45]
	v_mfma_f32_16x16x32_bf16 v[30:33], v[138:141], v[186:189], v[30:33]
	v_mfma_f32_16x16x32_bf16 v[26:29], v[146:149], v[186:189], v[26:29]
	v_mfma_f32_16x16x32_bf16 v[14:17], v[138:141], v[194:197], v[14:17]
	v_mfma_f32_16x16x32_bf16 v[10:13], v[146:149], v[194:197], v[10:13]
	v_mfma_f32_16x16x32_bf16 v[62:65], v[142:145], v[174:177], v[62:65]
	v_mfma_f32_16x16x32_bf16 v[58:61], v[150:153], v[174:177], v[58:61]
	v_mfma_f32_16x16x32_bf16 v[46:49], v[142:145], v[182:185], v[46:49]
	v_mfma_f32_16x16x32_bf16 v[42:45], v[150:153], v[182:185], v[42:45]
	v_mfma_f32_16x16x32_bf16 v[30:33], v[142:145], v[190:193], v[30:33]
	v_mfma_f32_16x16x32_bf16 v[26:29], v[150:153], v[190:193], v[26:29]
	v_mfma_f32_16x16x32_bf16 v[14:17], v[142:145], v[198:201], v[14:17]
	v_mfma_f32_16x16x32_bf16 v[10:13], v[150:153], v[198:201], v[10:13]
	s_setprio 0
	s_setprio 1
	v_mfma_f32_16x16x32_bf16 v[54:57], v[154:157], v[170:173], v[54:57]
	v_mfma_f32_16x16x32_bf16 v[50:53], v[162:165], v[170:173], v[50:53]
	v_mfma_f32_16x16x32_bf16 v[38:41], v[154:157], v[178:181], v[38:41]
	v_mfma_f32_16x16x32_bf16 v[34:37], v[162:165], v[178:181], v[34:37]
	v_mfma_f32_16x16x32_bf16 v[22:25], v[154:157], v[186:189], v[22:25]
	v_mfma_f32_16x16x32_bf16 v[18:21], v[162:165], v[186:189], v[18:21]
	v_mfma_f32_16x16x32_bf16 v[6:9], v[154:157], v[194:197], v[6:9]
	v_mfma_f32_16x16x32_bf16 v[2:5], v[162:165], v[194:197], v[2:5]
	v_mfma_f32_16x16x32_bf16 v[54:57], v[158:161], v[174:177], v[54:57]
	v_mfma_f32_16x16x32_bf16 v[50:53], v[166:169], v[174:177], v[50:53]
	v_mfma_f32_16x16x32_bf16 v[38:41], v[158:161], v[182:185], v[38:41]
	v_mfma_f32_16x16x32_bf16 v[34:37], v[166:169], v[182:185], v[34:37]
	v_mfma_f32_16x16x32_bf16 v[22:25], v[158:161], v[190:193], v[22:25]
	v_mfma_f32_16x16x32_bf16 v[18:21], v[166:169], v[190:193], v[18:21]
	v_mfma_f32_16x16x32_bf16 v[6:9], v[158:161], v[198:201], v[6:9]
	v_mfma_f32_16x16x32_bf16 v[2:5], v[166:169], v[198:201], v[2:5]
	s_setprio 0
	s_barrier
	s_add_i32 s47, 0, 0x18000
	s_add_i32 s50, 0, 0x1c000
	ds_read_b128 v[138:141], v0 offset:32768
	ds_read_b128 v[142:145], v0 offset:33792
	ds_read_b128 v[146:149], v0 offset:34816
	ds_read_b128 v[150:153], v0 offset:35840
	ds_read_b128 v[154:157], v0 offset:49152
	ds_read_b128 v[158:161], v0 offset:50176
	ds_read_b128 v[162:165], v0 offset:51200
	ds_read_b128 v[166:169], v0 offset:52224
	s_add_u32 s48, s10, 0x40000
	s_mov_b32 m0, s25
	ds_read_b128 v[170:173], v137 offset:32768
	ds_read_b128 v[174:177], v137 offset:33792
	ds_read_b128 v[178:181], v137 offset:34816
	ds_read_b128 v[182:185], v137 offset:35840
	ds_read_b128 v[186:189], v137 offset:36864
	ds_read_b128 v[190:193], v137 offset:37888
	ds_read_b128 v[194:197], v137 offset:38912
	ds_read_b128 v[198:201], v137 offset:39936
	s_addc_u32 s49, s11, 0
	s_nop 0
	global_load_lds_dwordx4 v130, s[48:49]
	s_mov_b32 m0, s26
	s_nop 0
	global_load_lds_dwordx4 v132, s[48:49]
	s_waitcnt vmcnt(8)
	s_waitcnt lgkmcnt(0)
	s_setprio 1
	s_barrier
	v_mfma_f32_16x16x32_bf16 v[126:129], v[138:141], v[170:173], v[126:129]
	v_mfma_f32_16x16x32_bf16 v[122:125], v[146:149], v[170:173], v[122:125]
	v_mfma_f32_16x16x32_bf16 v[110:113], v[138:141], v[178:181], v[110:113]
	v_mfma_f32_16x16x32_bf16 v[106:109], v[146:149], v[178:181], v[106:109]
	v_mfma_f32_16x16x32_bf16 v[94:97], v[138:141], v[186:189], v[94:97]
	v_mfma_f32_16x16x32_bf16 v[90:93], v[146:149], v[186:189], v[90:93]
	v_mfma_f32_16x16x32_bf16 v[78:81], v[138:141], v[194:197], v[78:81]
	v_mfma_f32_16x16x32_bf16 v[74:77], v[146:149], v[194:197], v[74:77]
	v_mfma_f32_16x16x32_bf16 v[126:129], v[142:145], v[174:177], v[126:129]
	v_mfma_f32_16x16x32_bf16 v[122:125], v[150:153], v[174:177], v[122:125]
	v_mfma_f32_16x16x32_bf16 v[110:113], v[142:145], v[182:185], v[110:113]
	v_mfma_f32_16x16x32_bf16 v[106:109], v[150:153], v[182:185], v[106:109]
	v_mfma_f32_16x16x32_bf16 v[94:97], v[142:145], v[190:193], v[94:97]
	v_mfma_f32_16x16x32_bf16 v[90:93], v[150:153], v[190:193], v[90:93]
	v_mfma_f32_16x16x32_bf16 v[78:81], v[142:145], v[198:201], v[78:81]
	v_mfma_f32_16x16x32_bf16 v[74:77], v[150:153], v[198:201], v[74:77]
	s_setprio 0
	s_setprio 1
	v_mfma_f32_16x16x32_bf16 v[118:121], v[154:157], v[170:173], v[118:121]
	v_mfma_f32_16x16x32_bf16 v[114:117], v[162:165], v[170:173], v[114:117]
	v_mfma_f32_16x16x32_bf16 v[102:105], v[154:157], v[178:181], v[102:105]
	v_mfma_f32_16x16x32_bf16 v[98:101], v[162:165], v[178:181], v[98:101]
	v_mfma_f32_16x16x32_bf16 v[86:89], v[154:157], v[186:189], v[86:89]
	v_mfma_f32_16x16x32_bf16 v[82:85], v[162:165], v[186:189], v[82:85]
	v_mfma_f32_16x16x32_bf16 v[70:73], v[154:157], v[194:197], v[70:73]
	v_mfma_f32_16x16x32_bf16 v[66:69], v[162:165], v[194:197], v[66:69]
	v_mfma_f32_16x16x32_bf16 v[118:121], v[158:161], v[174:177], v[118:121]
	v_mfma_f32_16x16x32_bf16 v[114:117], v[166:169], v[174:177], v[114:117]
	v_mfma_f32_16x16x32_bf16 v[102:105], v[158:161], v[182:185], v[102:105]
	v_mfma_f32_16x16x32_bf16 v[98:101], v[166:169], v[182:185], v[98:101]
	v_mfma_f32_16x16x32_bf16 v[86:89], v[158:161], v[190:193], v[86:89]
	v_mfma_f32_16x16x32_bf16 v[82:85], v[166:169], v[190:193], v[82:85]
	v_mfma_f32_16x16x32_bf16 v[70:73], v[158:161], v[198:201], v[70:73]
	v_mfma_f32_16x16x32_bf16 v[66:69], v[166:169], v[198:201], v[66:69]
	s_setprio 0
	s_barrier
	ds_read_b128 v[170:173], v137 offset:49152
	ds_read_b128 v[174:177], v137 offset:50176
	ds_read_b128 v[178:181], v137 offset:51200
	ds_read_b128 v[182:185], v137 offset:52224
	ds_read_b128 v[186:189], v137 offset:53248
	ds_read_b128 v[190:193], v137 offset:54272
	ds_read_b128 v[194:197], v137 offset:55296
	ds_read_b128 v[198:201], v137 offset:56320
	s_add_i32 s47, s47, s22
	s_add_u32 s100, s12, s38
	s_addc_u32 s101, s13, s39
	s_mov_b32 m0, s47
	s_nop 0
	global_load_lds_dwordx4 v134, s[100:101]
	s_add_i32 m0, s47, 0x2000
	s_nop 0
	s_add_u32 s12, s12, 0x40080
	s_addc_u32 s13, s13, 0
	s_add_i32 s47, s50, s22
	global_load_lds_dwordx4 v135, s[100:101]
	s_mov_b32 m0, s47
	s_nop 0
	global_load_lds_dwordx4 v134, s[12:13]
	s_add_i32 m0, s47, 0x2000
	s_nop 0
	global_load_lds_dwordx4 v135, s[12:13]
	s_mov_b32 m0, s42
	s_add_u32 s100, s10, s38
	s_addc_u32 s101, s11, s39
	v_mov_b32_e32 v0, v132
	global_load_lds_dwordx4 v130, s[100:101]
	s_mov_b32 m0, s43
	s_nop 0
	global_load_lds_dwordx4 v132, s[100:101]
	s_waitcnt vmcnt(8)
	s_waitcnt lgkmcnt(0)
	s_setprio 1
	s_barrier
	v_mfma_f32_16x16x32_bf16 v[62:65], v[138:141], v[170:173], v[62:65]
	v_mfma_f32_16x16x32_bf16 v[58:61], v[146:149], v[170:173], v[58:61]
	v_mfma_f32_16x16x32_bf16 v[46:49], v[138:141], v[178:181], v[46:49]
	v_mfma_f32_16x16x32_bf16 v[42:45], v[146:149], v[178:181], v[42:45]
	v_mfma_f32_16x16x32_bf16 v[30:33], v[138:141], v[186:189], v[30:33]
	v_mfma_f32_16x16x32_bf16 v[26:29], v[146:149], v[186:189], v[26:29]
	v_mfma_f32_16x16x32_bf16 v[14:17], v[138:141], v[194:197], v[14:17]
	v_mfma_f32_16x16x32_bf16 v[10:13], v[146:149], v[194:197], v[10:13]
	v_mfma_f32_16x16x32_bf16 v[62:65], v[142:145], v[174:177], v[62:65]
	v_mfma_f32_16x16x32_bf16 v[58:61], v[150:153], v[174:177], v[58:61]
	v_mfma_f32_16x16x32_bf16 v[46:49], v[142:145], v[182:185], v[46:49]
	v_mfma_f32_16x16x32_bf16 v[42:45], v[150:153], v[182:185], v[42:45]
	v_mfma_f32_16x16x32_bf16 v[30:33], v[142:145], v[190:193], v[30:33]
	v_mfma_f32_16x16x32_bf16 v[26:29], v[150:153], v[190:193], v[26:29]
	v_mfma_f32_16x16x32_bf16 v[14:17], v[142:145], v[198:201], v[14:17]
	v_mfma_f32_16x16x32_bf16 v[10:13], v[150:153], v[198:201], v[10:13]
	s_setprio 0
	s_setprio 1
	v_mfma_f32_16x16x32_bf16 v[54:57], v[154:157], v[170:173], v[54:57]
	v_mfma_f32_16x16x32_bf16 v[50:53], v[162:165], v[170:173], v[50:53]
	v_mfma_f32_16x16x32_bf16 v[38:41], v[154:157], v[178:181], v[38:41]
	v_mfma_f32_16x16x32_bf16 v[34:37], v[162:165], v[178:181], v[34:37]
	v_mfma_f32_16x16x32_bf16 v[22:25], v[154:157], v[186:189], v[22:25]
	v_mfma_f32_16x16x32_bf16 v[18:21], v[162:165], v[186:189], v[18:21]
	v_mfma_f32_16x16x32_bf16 v[6:9], v[154:157], v[194:197], v[6:9]
	v_mfma_f32_16x16x32_bf16 v[2:5], v[162:165], v[194:197], v[2:5]
	v_mfma_f32_16x16x32_bf16 v[54:57], v[158:161], v[174:177], v[54:57]
	v_mfma_f32_16x16x32_bf16 v[50:53], v[166:169], v[174:177], v[50:53]
	v_mfma_f32_16x16x32_bf16 v[38:41], v[158:161], v[182:185], v[38:41]
	v_mfma_f32_16x16x32_bf16 v[34:37], v[166:169], v[182:185], v[34:37]
	v_mfma_f32_16x16x32_bf16 v[22:25], v[158:161], v[190:193], v[22:25]
	v_mfma_f32_16x16x32_bf16 v[18:21], v[166:169], v[190:193], v[18:21]
	v_mfma_f32_16x16x32_bf16 v[6:9], v[158:161], v[198:201], v[6:9]
	v_mfma_f32_16x16x32_bf16 v[2:5], v[166:169], v[198:201], v[2:5]
	s_setprio 0
	s_barrier
	s_add_i32 s46, s46, 2
	s_add_u32 s2, s2, 0x100
	s_addc_u32 s3, s3, 0
	s_cmp_gt_u32 s46, 13
	s_cbranch_scc0 .LBB0_1681

.LBB0_1807:
	s_add_u32 s68, s4, s14
	s_addc_u32 s69, s5, s15
	s_add_u32 s16, s68, 0x100
	s_addc_u32 s17, s69, 0
	s_add_u32 s22, s50, s14
	s_addc_u32 s23, s51, s15
	s_add_i32 s67, 0, 0x10000
	s_cmp_eq_u32 s66, 12
	s_cselect_b32 s17, s5, s17
	s_cselect_b32 s16, s4, s16
	v_add_u32_e32 v0, s67, v126
	s_cselect_b32 s23, s13, s23
	s_cselect_b32 s22, s12, s22
	s_add_i32 s70, 0, 0x14000
	ds_read_b128 v[128:131], v0
	ds_read_b128 v[142:145], v0 offset:1024
	ds_read_b128 v[146:149], v0 offset:2048
	ds_read_b128 v[150:153], v0 offset:3072
	ds_read_b128 v[154:157], v0 offset:16384
	ds_read_b128 v[160:163], v0 offset:17408
	ds_read_b128 v[164:167], v0 offset:18432
	ds_read_b128 v[168:171], v0 offset:19456
	ds_read_b128 v[172:175], v127
	ds_read_b128 v[176:179], v127 offset:1024
	ds_read_b128 v[180:183], v127 offset:2048
	ds_read_b128 v[184:187], v127 offset:3072
	ds_read_b128 v[188:191], v127 offset:4096
	ds_read_b128 v[192:195], v127 offset:5120
	ds_read_b128 v[196:199], v127 offset:6144
	ds_read_b128 v[200:203], v127 offset:7168
	s_add_i32 m0, s43, 0xc000
	s_add_u32 s100, s68, s56
	s_addc_u32 s101, s69, s57
	global_load_lds_dwordx4 v122, s[100:101]
	s_add_i32 m0, s43, 0xe000
	s_nop 0
	global_load_lds_dwordx4 v123, s[100:101]
	s_waitcnt vmcnt(8)
	s_waitcnt lgkmcnt(0)
	s_setprio 1
	s_barrier
	v_mfma_f32_16x16x32_bf16 v[138:141], v[128:131], v[172:175], v[138:141]
	v_mfma_f32_16x16x32_bf16 v[132:135], v[146:149], v[172:175], v[134:137]
	v_mfma_f32_16x16x32_bf16 v[110:113], v[128:131], v[180:183], v[110:113]
	v_mfma_f32_16x16x32_bf16 v[106:109], v[146:149], v[180:183], v[106:109]
	v_mfma_f32_16x16x32_bf16 v[94:97], v[128:131], v[188:191], v[94:97]
	v_mfma_f32_16x16x32_bf16 v[90:93], v[146:149], v[188:191], v[90:93]
	v_mfma_f32_16x16x32_bf16 v[78:81], v[128:131], v[196:199], v[78:81]
	v_mfma_f32_16x16x32_bf16 v[74:77], v[146:149], v[196:199], v[74:77]
	v_mfma_f32_16x16x32_bf16 v[138:141], v[142:145], v[176:179], v[138:141]
	v_mfma_f32_16x16x32_bf16 v[132:135], v[150:153], v[176:179], v[132:135]
	v_mfma_f32_16x16x32_bf16 v[110:113], v[142:145], v[184:187], v[110:113]
	v_mfma_f32_16x16x32_bf16 v[106:109], v[150:153], v[184:187], v[106:109]
	v_mfma_f32_16x16x32_bf16 v[94:97], v[142:145], v[192:195], v[94:97]
	v_mfma_f32_16x16x32_bf16 v[90:93], v[150:153], v[192:195], v[90:93]
	v_mfma_f32_16x16x32_bf16 v[78:81], v[142:145], v[200:203], v[78:81]
	v_mfma_f32_16x16x32_bf16 v[74:77], v[150:153], v[200:203], v[74:77]
	s_setprio 0
	s_setprio 1
	v_mfma_f32_16x16x32_bf16 v[118:121], v[154:157], v[172:175], v[118:121]
	v_mfma_f32_16x16x32_bf16 v[114:117], v[164:167], v[172:175], v[114:117]
	v_mfma_f32_16x16x32_bf16 v[102:105], v[154:157], v[180:183], v[102:105]
	v_mfma_f32_16x16x32_bf16 v[98:101], v[164:167], v[180:183], v[98:101]
	v_mfma_f32_16x16x32_bf16 v[86:89], v[154:157], v[188:191], v[86:89]
	v_mfma_f32_16x16x32_bf16 v[82:85], v[164:167], v[188:191], v[82:85]
	v_mfma_f32_16x16x32_bf16 v[70:73], v[154:157], v[196:199], v[70:73]
	v_mfma_f32_16x16x32_bf16 v[66:69], v[164:167], v[196:199], v[66:69]
	v_mfma_f32_16x16x32_bf16 v[118:121], v[160:163], v[176:179], v[118:121]
	v_mfma_f32_16x16x32_bf16 v[114:117], v[168:171], v[176:179], v[114:117]
	v_mfma_f32_16x16x32_bf16 v[102:105], v[160:163], v[184:187], v[102:105]
	v_mfma_f32_16x16x32_bf16 v[98:101], v[168:171], v[184:187], v[98:101]
	v_mfma_f32_16x16x32_bf16 v[86:89], v[160:163], v[192:195], v[86:89]
	v_mfma_f32_16x16x32_bf16 v[82:85], v[168:171], v[192:195], v[82:85]
	v_mfma_f32_16x16x32_bf16 v[70:73], v[160:163], v[200:203], v[70:73]
	v_mfma_f32_16x16x32_bf16 v[66:69], v[168:171], v[200:203], v[66:69]
	s_setprio 0
	s_barrier
	s_add_i32 s67, s67, s42
	ds_read_b128 v[172:175], v127 offset:16384
	ds_read_b128 v[176:179], v127 offset:17408
	ds_read_b128 v[180:183], v127 offset:18432
	ds_read_b128 v[184:187], v127 offset:19456
	ds_read_b128 v[188:191], v127 offset:20480
	ds_read_b128 v[192:195], v127 offset:21504
	ds_read_b128 v[196:199], v127 offset:22528
	ds_read_b128 v[200:203], v127 offset:23552
	s_mov_b32 m0, s67
	s_nop 0
	global_load_lds_dwordx4 v124, s[22:23]
	s_add_i32 m0, s67, 0x2000
	s_add_u32 s68, s22, 0x40000
	global_load_lds_dwordx4 v125, s[22:23]
	s_addc_u32 s69, s23, 0
	s_add_i32 s67, s70, s42
	s_mov_b32 m0, s67
	s_nop 0
	global_load_lds_dwordx4 v124, s[68:69]
	s_add_i32 m0, s67, 0x2000
	s_nop 0
	global_load_lds_dwordx4 v125, s[68:69]
	s_mov_b32 m0, s43
	s_nop 0
	global_load_lds_dwordx4 v122, s[16:17]
	s_mov_b32 m0, s46
	s_nop 0
	global_load_lds_dwordx4 v123, s[16:17]
	s_waitcnt vmcnt(8)
	s_waitcnt lgkmcnt(0)
	s_setprio 1
	s_barrier
	v_mfma_f32_16x16x32_bf16 v[62:65], v[128:131], v[172:175], v[62:65]
	v_mfma_f32_16x16x32_bf16 v[58:61], v[146:149], v[172:175], v[58:61]
	v_mfma_f32_16x16x32_bf16 v[46:49], v[128:131], v[180:183], v[46:49]
	v_mfma_f32_16x16x32_bf16 v[42:45], v[146:149], v[180:183], v[42:45]
	v_mfma_f32_16x16x32_bf16 v[30:33], v[128:131], v[188:191], v[30:33]
	v_mfma_f32_16x16x32_bf16 v[26:29], v[146:149], v[188:191], v[26:29]
	v_mfma_f32_16x16x32_bf16 v[14:17], v[128:131], v[196:199], v[14:17]
	v_mfma_f32_16x16x32_bf16 v[10:13], v[146:149], v[196:199], v[10:13]
	v_mfma_f32_16x16x32_bf16 v[62:65], v[142:145], v[176:179], v[62:65]
	v_mfma_f32_16x16x32_bf16 v[58:61], v[150:153], v[176:179], v[58:61]
	v_mfma_f32_16x16x32_bf16 v[46:49], v[142:145], v[184:187], v[46:49]
	v_mfma_f32_16x16x32_bf16 v[42:45], v[150:153], v[184:187], v[42:45]
	v_mfma_f32_16x16x32_bf16 v[30:33], v[142:145], v[192:195], v[30:33]
	v_mfma_f32_16x16x32_bf16 v[26:29], v[150:153], v[192:195], v[26:29]
	v_mfma_f32_16x16x32_bf16 v[14:17], v[142:145], v[200:203], v[14:17]
	v_mfma_f32_16x16x32_bf16 v[10:13], v[150:153], v[200:203], v[10:13]
	s_setprio 0
	s_setprio 1
	v_mfma_f32_16x16x32_bf16 v[54:57], v[154:157], v[172:175], v[54:57]
	v_mfma_f32_16x16x32_bf16 v[50:53], v[164:167], v[172:175], v[50:53]
	v_mfma_f32_16x16x32_bf16 v[38:41], v[154:157], v[180:183], v[38:41]
	v_mfma_f32_16x16x32_bf16 v[34:37], v[164:167], v[180:183], v[34:37]
	v_mfma_f32_16x16x32_bf16 v[22:25], v[154:157], v[188:191], v[22:25]
	v_mfma_f32_16x16x32_bf16 v[18:21], v[164:167], v[188:191], v[18:21]
	v_mfma_f32_16x16x32_bf16 v[6:9], v[154:157], v[196:199], v[6:9]
	v_mfma_f32_16x16x32_bf16 v[2:5], v[164:167], v[196:199], v[2:5]
	v_mfma_f32_16x16x32_bf16 v[54:57], v[160:163], v[176:179], v[54:57]
	v_mfma_f32_16x16x32_bf16 v[50:53], v[168:171], v[176:179], v[50:53]
	v_mfma_f32_16x16x32_bf16 v[38:41], v[160:163], v[184:187], v[38:41]
	v_mfma_f32_16x16x32_bf16 v[34:37], v[168:171], v[184:187], v[34:37]
	v_mfma_f32_16x16x32_bf16 v[22:25], v[160:163], v[192:195], v[22:25]
	v_mfma_f32_16x16x32_bf16 v[18:21], v[168:171], v[192:195], v[18:21]
	v_mfma_f32_16x16x32_bf16 v[6:9], v[160:163], v[200:203], v[6:9]
	v_mfma_f32_16x16x32_bf16 v[2:5], v[168:171], v[200:203], v[2:5]
	s_setprio 0
	s_barrier
	s_add_i32 s67, 0, 0x18000
	s_add_i32 s70, 0, 0x1c000
	ds_read_b128 v[128:131], v0 offset:32768
	ds_read_b128 v[142:145], v0 offset:33792
	ds_read_b128 v[146:149], v0 offset:34816
	ds_read_b128 v[150:153], v0 offset:35840
	ds_read_b128 v[154:157], v0 offset:49152
	ds_read_b128 v[160:163], v0 offset:50176
	ds_read_b128 v[164:167], v0 offset:51200
	ds_read_b128 v[168:171], v0 offset:52224
	s_add_u32 s68, s16, 0x40000
	s_mov_b32 m0, s47
	ds_read_b128 v[172:175], v127 offset:32768
	ds_read_b128 v[176:179], v127 offset:33792
	ds_read_b128 v[180:183], v127 offset:34816
	ds_read_b128 v[184:187], v127 offset:35840
	ds_read_b128 v[188:191], v127 offset:36864
	ds_read_b128 v[192:195], v127 offset:37888
	ds_read_b128 v[196:199], v127 offset:38912
	ds_read_b128 v[200:203], v127 offset:39936
	s_addc_u32 s69, s17, 0
	s_nop 0
	global_load_lds_dwordx4 v122, s[68:69]
	s_mov_b32 m0, s48
	s_nop 0
	global_load_lds_dwordx4 v123, s[68:69]
	s_waitcnt vmcnt(8)
	s_waitcnt lgkmcnt(0)
	s_setprio 1
	s_barrier
	v_mfma_f32_16x16x32_bf16 v[136:139], v[128:131], v[172:175], v[138:141]
	v_mfma_f32_16x16x32_bf16 v[132:135], v[146:149], v[172:175], v[132:135]
	v_mfma_f32_16x16x32_bf16 v[110:113], v[128:131], v[180:183], v[110:113]
	v_mfma_f32_16x16x32_bf16 v[106:109], v[146:149], v[180:183], v[106:109]
	v_mfma_f32_16x16x32_bf16 v[94:97], v[128:131], v[188:191], v[94:97]
	v_mfma_f32_16x16x32_bf16 v[90:93], v[146:149], v[188:191], v[90:93]
	v_mfma_f32_16x16x32_bf16 v[78:81], v[128:131], v[196:199], v[78:81]
	v_mfma_f32_16x16x32_bf16 v[74:77], v[146:149], v[196:199], v[74:77]
	v_mfma_f32_16x16x32_bf16 v[138:141], v[142:145], v[176:179], v[136:139]
	v_mfma_f32_16x16x32_bf16 v[134:137], v[150:153], v[176:179], v[132:135]
	v_mfma_f32_16x16x32_bf16 v[110:113], v[142:145], v[184:187], v[110:113]
	v_mfma_f32_16x16x32_bf16 v[106:109], v[150:153], v[184:187], v[106:109]
	v_mfma_f32_16x16x32_bf16 v[94:97], v[142:145], v[192:195], v[94:97]
	v_mfma_f32_16x16x32_bf16 v[90:93], v[150:153], v[192:195], v[90:93]
	v_mfma_f32_16x16x32_bf16 v[78:81], v[142:145], v[200:203], v[78:81]
	v_mfma_f32_16x16x32_bf16 v[74:77], v[150:153], v[200:203], v[74:77]
	s_setprio 0
	s_setprio 1
	v_mfma_f32_16x16x32_bf16 v[118:121], v[154:157], v[172:175], v[118:121]
	v_mfma_f32_16x16x32_bf16 v[114:117], v[164:167], v[172:175], v[114:117]
	v_mfma_f32_16x16x32_bf16 v[102:105], v[154:157], v[180:183], v[102:105]
	v_mfma_f32_16x16x32_bf16 v[98:101], v[164:167], v[180:183], v[98:101]
	v_mfma_f32_16x16x32_bf16 v[86:89], v[154:157], v[188:191], v[86:89]
	v_mfma_f32_16x16x32_bf16 v[82:85], v[164:167], v[188:191], v[82:85]
	v_mfma_f32_16x16x32_bf16 v[70:73], v[154:157], v[196:199], v[70:73]
	v_mfma_f32_16x16x32_bf16 v[66:69], v[164:167], v[196:199], v[66:69]
	v_mfma_f32_16x16x32_bf16 v[118:121], v[160:163], v[176:179], v[118:121]
	v_mfma_f32_16x16x32_bf16 v[114:117], v[168:171], v[176:179], v[114:117]
	v_mfma_f32_16x16x32_bf16 v[102:105], v[160:163], v[184:187], v[102:105]
	v_mfma_f32_16x16x32_bf16 v[98:101], v[168:171], v[184:187], v[98:101]
	v_mfma_f32_16x16x32_bf16 v[86:89], v[160:163], v[192:195], v[86:89]
	v_mfma_f32_16x16x32_bf16 v[82:85], v[168:171], v[192:195], v[82:85]
	v_mfma_f32_16x16x32_bf16 v[70:73], v[160:163], v[200:203], v[70:73]
	v_mfma_f32_16x16x32_bf16 v[66:69], v[168:171], v[200:203], v[66:69]
	s_setprio 0
	s_barrier
	ds_read_b128 v[172:175], v127 offset:49152
	ds_read_b128 v[176:179], v127 offset:50176
	ds_read_b128 v[180:183], v127 offset:51200
	ds_read_b128 v[184:187], v127 offset:52224
	ds_read_b128 v[188:191], v127 offset:53248
	ds_read_b128 v[192:195], v127 offset:54272
	ds_read_b128 v[196:199], v127 offset:55296
	ds_read_b128 v[200:203], v127 offset:56320
	s_add_i32 s67, s67, s42
	s_add_u32 s100, s22, s38
	s_addc_u32 s101, s23, s39
	s_mov_b32 m0, s67
	s_nop 0
	global_load_lds_dwordx4 v124, s[100:101]
	s_add_i32 m0, s67, 0x2000
	s_nop 0
	s_add_u32 s22, s22, 0x40080
	s_addc_u32 s23, s23, 0
	s_add_i32 s67, s70, s42
	global_load_lds_dwordx4 v125, s[100:101]
	s_mov_b32 m0, s67
	s_nop 0
	global_load_lds_dwordx4 v124, s[22:23]
	s_add_i32 m0, s67, 0x2000
	s_nop 0
	global_load_lds_dwordx4 v125, s[22:23]
	s_mov_b32 m0, s64
	s_add_u32 s100, s16, s38
	s_addc_u32 s101, s17, s39
	v_mov_b32_e32 v0, v123
	global_load_lds_dwordx4 v122, s[100:101]
	s_mov_b32 m0, s65
	s_nop 0
	global_load_lds_dwordx4 v123, s[100:101]
	s_waitcnt vmcnt(8)
	s_waitcnt lgkmcnt(0)
	s_setprio 1
	s_barrier
	v_mfma_f32_16x16x32_bf16 v[62:65], v[128:131], v[172:175], v[62:65]
	v_mfma_f32_16x16x32_bf16 v[58:61], v[146:149], v[172:175], v[58:61]
	v_mfma_f32_16x16x32_bf16 v[46:49], v[128:131], v[180:183], v[46:49]
	v_mfma_f32_16x16x32_bf16 v[42:45], v[146:149], v[180:183], v[42:45]
	v_mfma_f32_16x16x32_bf16 v[30:33], v[128:131], v[188:191], v[30:33]
	v_mfma_f32_16x16x32_bf16 v[26:29], v[146:149], v[188:191], v[26:29]
	v_mfma_f32_16x16x32_bf16 v[14:17], v[128:131], v[196:199], v[14:17]
	v_mfma_f32_16x16x32_bf16 v[10:13], v[146:149], v[196:199], v[10:13]
	v_mfma_f32_16x16x32_bf16 v[62:65], v[142:145], v[176:179], v[62:65]
	v_mfma_f32_16x16x32_bf16 v[58:61], v[150:153], v[176:179], v[58:61]
	v_mfma_f32_16x16x32_bf16 v[46:49], v[142:145], v[184:187], v[46:49]
	v_mfma_f32_16x16x32_bf16 v[42:45], v[150:153], v[184:187], v[42:45]
	v_mfma_f32_16x16x32_bf16 v[30:33], v[142:145], v[192:195], v[30:33]
	v_mfma_f32_16x16x32_bf16 v[26:29], v[150:153], v[192:195], v[26:29]
	v_mfma_f32_16x16x32_bf16 v[14:17], v[142:145], v[200:203], v[14:17]
	v_mfma_f32_16x16x32_bf16 v[10:13], v[150:153], v[200:203], v[10:13]
	s_setprio 0
	s_setprio 1
	v_mfma_f32_16x16x32_bf16 v[54:57], v[154:157], v[172:175], v[54:57]
	v_mfma_f32_16x16x32_bf16 v[50:53], v[164:167], v[172:175], v[50:53]
	v_mfma_f32_16x16x32_bf16 v[38:41], v[154:157], v[180:183], v[38:41]
	v_mfma_f32_16x16x32_bf16 v[34:37], v[164:167], v[180:183], v[34:37]
	v_mfma_f32_16x16x32_bf16 v[22:25], v[154:157], v[188:191], v[22:25]
	v_mfma_f32_16x16x32_bf16 v[18:21], v[164:167], v[188:191], v[18:21]
	v_mfma_f32_16x16x32_bf16 v[6:9], v[154:157], v[196:199], v[6:9]
	v_mfma_f32_16x16x32_bf16 v[2:5], v[164:167], v[196:199], v[2:5]
	v_mfma_f32_16x16x32_bf16 v[54:57], v[160:163], v[176:179], v[54:57]
	v_mfma_f32_16x16x32_bf16 v[50:53], v[168:171], v[176:179], v[50:53]
	v_mfma_f32_16x16x32_bf16 v[38:41], v[160:163], v[184:187], v[38:41]
	v_mfma_f32_16x16x32_bf16 v[34:37], v[168:171], v[184:187], v[34:37]
	v_mfma_f32_16x16x32_bf16 v[22:25], v[160:163], v[192:195], v[22:25]
	v_mfma_f32_16x16x32_bf16 v[18:21], v[168:171], v[192:195], v[18:21]
	v_mfma_f32_16x16x32_bf16 v[6:9], v[160:163], v[200:203], v[6:9]
	v_mfma_f32_16x16x32_bf16 v[2:5], v[168:171], v[200:203], v[2:5]
	s_setprio 0
	s_barrier
	s_add_i32 s66, s66, 2
	s_add_u32 s14, s14, 0x100
	s_addc_u32 s15, s15, 0
	s_cmp_gt_u32 s66, 13
	s_cbranch_scc0 .LBB0_1807

.LBB0_1829:
	s_or_b64 exec, exec, s[40:41]
	s_waitcnt lgkmcnt(0)
	s_mov_b32 s24, s100
	s_nop 0
	v_add_u32_e32 v0, s24, v0
	v_and_b32_e32 v2, 3, v0
	v_cmp_ne_u32_e32 vcc, 3, v2
	s_and_saveexec_b64 s[24:25], vcc
	s_cbranch_execz .LBB0_1843
	s_load_dword s100, s[22:23], 0x0 glc
	v_bitop3_b32 v0, v0, -4, v0 bitop3:0xc
	s_waitcnt lgkmcnt(0)
	v_add_u32_e32 v2, s100, v0
	v_cmp_gt_i32_e32 vcc, 0, v2
	s_and_b64 exec, exec, vcc
	s_cbranch_execz .LBB0_1843
	s_add_u32 s6, s6, 0x4200
	s_addc_u32 s7, s7, 0
	s_mov_b32 s26, 1
	s_mov_b64 s[40:41], 0
	s_branch .LBB0_1833

.LBB0_1911:
	s_or_b64 exec, exec, s[10:11]
	s_waitcnt lgkmcnt(0)
	s_mov_b32 s6, s100
	s_nop 0
	v_add_u32_e32 v0, s6, v0
	v_and_b32_e32 v2, 3, v0
	v_cmp_ne_u32_e32 vcc, 3, v2
	s_and_saveexec_b64 s[6:7], vcc
	s_cbranch_execz .LBB0_1925
	s_load_dword s100, s[4:5], 0x0 glc
	v_bitop3_b32 v0, v0, -4, v0 bitop3:0xc
	s_waitcnt lgkmcnt(0)
	v_add_u32_e32 v2, s100, v0
	v_cmp_gt_i32_e32 vcc, 0, v2
	s_and_b64 exec, exec, vcc
	s_cbranch_execz .LBB0_1925
	s_add_u32 s8, s8, 0x4200
	s_addc_u32 s9, s9, 0
	s_mov_b32 s24, 1
	s_mov_b64 s[10:11], 0
	s_branch .LBB0_1915
